# GEMM K loops: duplicate s_waitcnt lgkmcnt(0) before each MFMA block removed (on top of the removed setprio flips)
# speedup vs baseline: 1.0100x; 1.0019x over previous
.LBB0_118:
	ds_read_b128 v[128:131], v221
	ds_read_b128 v[132:135], v221 offset:1024
	ds_read_b128 v[136:139], v221 offset:2048
	ds_read_b128 v[140:143], v221 offset:3072
	s_add_u32 s8, s6, 0xfff80080
	s_addc_u32 s9, s7, -1
	s_cmp_eq_u32 s53, 28
	s_cselect_b32 s11, s5, s9
	s_cselect_b32 s10, s33, s8
	s_cselect_b32 s9, s43, s52
	s_cselect_b32 s8, s45, s51
	v_lshl_add_u64 v[198:199], s[6:7], 0, v[182:183]
	s_add_i32 m0, s58, 0xc000
	ds_read_b128 v[144:147], v222
	ds_read_b128 v[148:151], v222 offset:1024
	ds_read_b128 v[152:155], v222 offset:2048
	ds_read_b128 v[156:159], v222 offset:3072
	ds_read_b128 v[160:163], v222 offset:4096
	ds_read_b128 v[164:167], v222 offset:5120
	ds_read_b128 v[190:193], v222 offset:6144
	ds_read_b128 v[194:197], v222 offset:7168
	global_load_lds_dwordx4 v[198:199], off
	v_lshl_add_u64 v[198:199], s[6:7], 0, v[184:185]
	s_add_i32 m0, s58, 0xe000
	s_nop 0
	global_load_lds_dwordx4 v[198:199], off
	s_waitcnt lgkmcnt(8)
	s_barrier
	s_waitcnt lgkmcnt(0)


	v_mfma_f32_16x16x32_bf16 v[124:127], v[128:131], v[144:147], v[124:127]
	v_mfma_f32_16x16x32_bf16 v[116:119], v[136:139], v[144:147], v[116:119]
	v_mfma_f32_16x16x32_bf16 v[108:111], v[128:131], v[152:155], v[108:111]
	v_mfma_f32_16x16x32_bf16 v[100:103], v[136:139], v[152:155], v[100:103]
	v_mfma_f32_16x16x32_bf16 v[92:95], v[128:131], v[160:163], v[92:95]
	v_mfma_f32_16x16x32_bf16 v[84:87], v[136:139], v[160:163], v[84:87]
	v_mfma_f32_16x16x32_bf16 v[76:79], v[128:131], v[190:193], v[76:79]
	v_mfma_f32_16x16x32_bf16 v[68:71], v[136:139], v[190:193], v[68:71]
	v_mfma_f32_16x16x32_bf16 v[124:127], v[132:135], v[148:151], v[124:127]
	v_mfma_f32_16x16x32_bf16 v[116:119], v[140:143], v[148:151], v[116:119]
	v_mfma_f32_16x16x32_bf16 v[108:111], v[132:135], v[156:159], v[108:111]
	v_mfma_f32_16x16x32_bf16 v[100:103], v[140:143], v[156:159], v[100:103]
	v_mfma_f32_16x16x32_bf16 v[92:95], v[132:135], v[164:167], v[92:95]
	v_mfma_f32_16x16x32_bf16 v[84:87], v[140:143], v[164:167], v[84:87]
	v_mfma_f32_16x16x32_bf16 v[76:79], v[132:135], v[194:197], v[76:79]
	v_mfma_f32_16x16x32_bf16 v[68:71], v[140:143], v[194:197], v[68:71]

	s_barrier
	s_add_i32 s54, s81, s57
	v_lshl_add_u64 v[230:231], s[8:9], 0, v[172:173]
	s_mov_b32 m0, s54
	ds_read_b128 v[198:201], v223
	ds_read_b128 v[202:205], v223 offset:1024
	ds_read_b128 v[206:209], v223 offset:2048
	ds_read_b128 v[226:229], v223 offset:3072
	global_load_lds_dwordx4 v[230:231], off
	v_lshl_add_u64 v[232:233], s[8:9], 0, v[174:175]
	s_add_i32 m0, s54, 0x2000
	s_nop 0
	global_load_lds_dwordx4 v[232:233], off
	s_barrier
	s_waitcnt lgkmcnt(0)


	v_mfma_f32_16x16x32_bf16 v[120:123], v[198:201], v[144:147], v[120:123]
	v_mfma_f32_16x16x32_bf16 v[112:115], v[206:209], v[144:147], v[112:115]
	v_mfma_f32_16x16x32_bf16 v[104:107], v[198:201], v[152:155], v[104:107]
	v_mfma_f32_16x16x32_bf16 v[96:99], v[206:209], v[152:155], v[96:99]
	v_mfma_f32_16x16x32_bf16 v[88:91], v[198:201], v[160:163], v[88:91]
	v_mfma_f32_16x16x32_bf16 v[80:83], v[206:209], v[160:163], v[80:83]
	v_mfma_f32_16x16x32_bf16 v[72:75], v[198:201], v[190:193], v[72:75]
	v_mfma_f32_16x16x32_bf16 v[64:67], v[206:209], v[190:193], v[64:67]
	v_mfma_f32_16x16x32_bf16 v[120:123], v[202:205], v[148:151], v[120:123]
	v_mfma_f32_16x16x32_bf16 v[112:115], v[226:229], v[148:151], v[112:115]
	v_mfma_f32_16x16x32_bf16 v[104:107], v[202:205], v[156:159], v[104:107]
	v_mfma_f32_16x16x32_bf16 v[96:99], v[226:229], v[156:159], v[96:99]
	v_mfma_f32_16x16x32_bf16 v[88:91], v[202:205], v[164:167], v[88:91]
	v_mfma_f32_16x16x32_bf16 v[80:83], v[226:229], v[164:167], v[80:83]
	v_mfma_f32_16x16x32_bf16 v[72:75], v[202:205], v[194:197], v[72:75]
	v_mfma_f32_16x16x32_bf16 v[64:67], v[226:229], v[194:197], v[64:67]

	s_mov_b32 m0, s58
	v_lshl_add_u64 v[234:235], s[10:11], 0, v[172:173]
	s_barrier
	ds_read_b128 v[144:147], v222 offset:16384
	ds_read_b128 v[148:151], v222 offset:17408
	ds_read_b128 v[152:155], v222 offset:18432
	ds_read_b128 v[156:159], v222 offset:19456
	ds_read_b128 v[160:163], v222 offset:20480
	ds_read_b128 v[164:167], v222 offset:21504
	ds_read_b128 v[190:193], v222 offset:22528
	ds_read_b128 v[194:197], v222 offset:23552
	global_load_lds_dwordx4 v[234:235], off
	v_lshl_add_u64 v[236:237], s[10:11], 0, v[174:175]
	s_mov_b32 m0, s59
	s_nop 0
	global_load_lds_dwordx4 v[236:237], off
	s_barrier
	s_waitcnt lgkmcnt(0)


	v_mfma_f32_16x16x32_bf16 v[60:63], v[128:131], v[144:147], v[60:63]
	v_mfma_f32_16x16x32_bf16 v[52:55], v[136:139], v[144:147], v[52:55]
	v_mfma_f32_16x16x32_bf16 v[44:47], v[128:131], v[152:155], v[44:47]
	v_mfma_f32_16x16x32_bf16 v[36:39], v[136:139], v[152:155], v[36:39]
	v_mfma_f32_16x16x32_bf16 v[28:31], v[128:131], v[160:163], v[28:31]
	v_mfma_f32_16x16x32_bf16 v[20:23], v[136:139], v[160:163], v[20:23]
	v_mfma_f32_16x16x32_bf16 v[12:15], v[128:131], v[190:193], v[12:15]
	v_mfma_f32_16x16x32_bf16 v[4:7], v[136:139], v[190:193], v[4:7]
	v_mfma_f32_16x16x32_bf16 v[60:63], v[132:135], v[148:151], v[60:63]
	v_mfma_f32_16x16x32_bf16 v[52:55], v[140:143], v[148:151], v[52:55]
	v_mfma_f32_16x16x32_bf16 v[44:47], v[132:135], v[156:159], v[44:47]
	v_mfma_f32_16x16x32_bf16 v[36:39], v[140:143], v[156:159], v[36:39]
	v_mfma_f32_16x16x32_bf16 v[28:31], v[132:135], v[164:167], v[28:31]
	v_mfma_f32_16x16x32_bf16 v[20:23], v[140:143], v[164:167], v[20:23]
	v_mfma_f32_16x16x32_bf16 v[12:15], v[132:135], v[194:197], v[12:15]
	v_mfma_f32_16x16x32_bf16 v[4:7], v[140:143], v[194:197], v[4:7]

	s_barrier
	s_add_u32 s54, s8, 0x80000
	s_addc_u32 s55, s9, 0
	s_add_i32 vcc_lo, s30, s57
	v_lshl_add_u64 v[128:129], s[54:55], 0, v[172:173]
	s_mov_b32 m0, vcc_lo
	s_nop 0
	global_load_lds_dwordx4 v[128:129], off
	v_lshl_add_u64 v[128:129], s[54:55], 0, v[174:175]
	s_add_i32 m0, vcc_lo, 0x2000
	s_nop 0
	global_load_lds_dwordx4 v[128:129], off
	s_waitcnt vmcnt(6)
	s_barrier

	v_mfma_f32_16x16x32_bf16 v[56:59], v[198:201], v[144:147], v[56:59]
	v_mfma_f32_16x16x32_bf16 v[48:51], v[206:209], v[144:147], v[48:51]
	v_mfma_f32_16x16x32_bf16 v[40:43], v[198:201], v[152:155], v[40:43]
	v_mfma_f32_16x16x32_bf16 v[32:35], v[206:209], v[152:155], v[32:35]
	v_mfma_f32_16x16x32_bf16 v[24:27], v[198:201], v[160:163], v[24:27]
	v_mfma_f32_16x16x32_bf16 v[16:19], v[206:209], v[160:163], v[16:19]
	v_mfma_f32_16x16x32_bf16 v[8:11], v[198:201], v[190:193], v[8:11]
	v_mfma_f32_16x16x32_bf16 v[0:3], v[206:209], v[190:193], v[0:3]
	v_mfma_f32_16x16x32_bf16 v[56:59], v[202:205], v[148:151], v[56:59]
	v_mfma_f32_16x16x32_bf16 v[48:51], v[226:229], v[148:151], v[48:51]
	v_mfma_f32_16x16x32_bf16 v[40:43], v[202:205], v[156:159], v[40:43]
	v_mfma_f32_16x16x32_bf16 v[32:35], v[226:229], v[156:159], v[32:35]
	v_mfma_f32_16x16x32_bf16 v[24:27], v[202:205], v[164:167], v[24:27]
	v_mfma_f32_16x16x32_bf16 v[16:19], v[226:229], v[164:167], v[16:19]
	v_mfma_f32_16x16x32_bf16 v[8:11], v[202:205], v[194:197], v[8:11]
	v_mfma_f32_16x16x32_bf16 v[0:3], v[226:229], v[194:197], v[0:3]

	s_add_i32 s54, 0, 0x18000
	v_add_u32_e32 v140, s54, v179
	s_barrier
	ds_read_b128 v[128:131], v140
	ds_read_b128 v[132:135], v140 offset:1024
	ds_read_b128 v[136:139], v140 offset:2048
	ds_read_b128 v[140:143], v140 offset:3072
	s_add_u32 s10, s10, 0x80000
	s_addc_u32 s11, s11, 0
	s_mov_b32 m0, s2
	v_lshl_add_u64 v[198:199], s[10:11], 0, v[172:173]
	ds_read_b128 v[144:147], v222 offset:32768
	ds_read_b128 v[148:151], v222 offset:33792
	ds_read_b128 v[152:155], v222 offset:34816
	ds_read_b128 v[156:159], v222 offset:35840
	ds_read_b128 v[160:163], v222 offset:36864
	ds_read_b128 v[164:167], v222 offset:37888
	ds_read_b128 v[190:193], v222 offset:38912
	ds_read_b128 v[194:197], v222 offset:39936
	global_load_lds_dwordx4 v[198:199], off
	v_lshl_add_u64 v[198:199], s[10:11], 0, v[174:175]
	s_mov_b32 m0, s3
	s_nop 0
	global_load_lds_dwordx4 v[198:199], off
	s_waitcnt lgkmcnt(8)
	s_barrier
	s_waitcnt lgkmcnt(0)


	v_mfma_f32_16x16x32_bf16 v[124:127], v[128:131], v[144:147], v[124:127]
	v_mfma_f32_16x16x32_bf16 v[116:119], v[136:139], v[144:147], v[116:119]
	v_mfma_f32_16x16x32_bf16 v[108:111], v[128:131], v[152:155], v[108:111]
	v_mfma_f32_16x16x32_bf16 v[100:103], v[136:139], v[152:155], v[100:103]
	v_mfma_f32_16x16x32_bf16 v[92:95], v[128:131], v[160:163], v[92:95]
	v_mfma_f32_16x16x32_bf16 v[84:87], v[136:139], v[160:163], v[84:87]
	v_mfma_f32_16x16x32_bf16 v[76:79], v[128:131], v[190:193], v[76:79]
	v_mfma_f32_16x16x32_bf16 v[68:71], v[136:139], v[190:193], v[68:71]
	v_mfma_f32_16x16x32_bf16 v[124:127], v[132:135], v[148:151], v[124:127]
	v_mfma_f32_16x16x32_bf16 v[116:119], v[140:143], v[148:151], v[116:119]
	v_mfma_f32_16x16x32_bf16 v[108:111], v[132:135], v[156:159], v[108:111]
	v_mfma_f32_16x16x32_bf16 v[100:103], v[140:143], v[156:159], v[100:103]
	v_mfma_f32_16x16x32_bf16 v[92:95], v[132:135], v[164:167], v[92:95]
	v_mfma_f32_16x16x32_bf16 v[84:87], v[140:143], v[164:167], v[84:87]
	v_mfma_f32_16x16x32_bf16 v[76:79], v[132:135], v[194:197], v[76:79]
	v_mfma_f32_16x16x32_bf16 v[68:71], v[140:143], v[194:197], v[68:71]

	s_barrier
	s_add_i32 s10, 0, 0x1c000
	s_add_i32 s11, s54, s57
	v_add_u32_e32 v180, s10, v179
	v_lshl_add_u64 v[230:231], v[230:231], 0, s[20:21]
	s_mov_b32 m0, s11
	ds_read_b128 v[198:201], v180
	ds_read_b128 v[202:205], v180 offset:1024
	ds_read_b128 v[206:209], v180 offset:2048
	ds_read_b128 v[226:229], v180 offset:3072
	global_load_lds_dwordx4 v[230:231], off
	v_lshl_add_u64 v[230:231], v[232:233], 0, s[20:21]
	s_add_i32 m0, s11, 0x2000
	s_nop 0
	global_load_lds_dwordx4 v[230:231], off
	s_barrier
	s_waitcnt lgkmcnt(0)


	v_mfma_f32_16x16x32_bf16 v[120:123], v[198:201], v[144:147], v[120:123]
	v_mfma_f32_16x16x32_bf16 v[112:115], v[206:209], v[144:147], v[112:115]
	v_mfma_f32_16x16x32_bf16 v[104:107], v[198:201], v[152:155], v[104:107]
	v_mfma_f32_16x16x32_bf16 v[96:99], v[206:209], v[152:155], v[96:99]
	v_mfma_f32_16x16x32_bf16 v[88:91], v[198:201], v[160:163], v[88:91]
	v_mfma_f32_16x16x32_bf16 v[80:83], v[206:209], v[160:163], v[80:83]
	v_mfma_f32_16x16x32_bf16 v[72:75], v[198:201], v[190:193], v[72:75]
	v_mfma_f32_16x16x32_bf16 v[64:67], v[206:209], v[190:193], v[64:67]
	v_mfma_f32_16x16x32_bf16 v[120:123], v[202:205], v[148:151], v[120:123]
	v_mfma_f32_16x16x32_bf16 v[112:115], v[226:229], v[148:151], v[112:115]
	v_mfma_f32_16x16x32_bf16 v[104:107], v[202:205], v[156:159], v[104:107]
	v_mfma_f32_16x16x32_bf16 v[96:99], v[226:229], v[156:159], v[96:99]
	v_mfma_f32_16x16x32_bf16 v[88:91], v[202:205], v[164:167], v[88:91]
	v_mfma_f32_16x16x32_bf16 v[80:83], v[226:229], v[164:167], v[80:83]
	v_mfma_f32_16x16x32_bf16 v[72:75], v[202:205], v[194:197], v[72:75]
	v_mfma_f32_16x16x32_bf16 v[64:67], v[226:229], v[194:197], v[64:67]

	s_mov_b32 m0, s96
	v_lshl_add_u64 v[230:231], v[234:235], 0, s[20:21]
	s_barrier
	ds_read_b128 v[144:147], v222 offset:49152
	ds_read_b128 v[148:151], v222 offset:50176
	ds_read_b128 v[152:155], v222 offset:51200
	ds_read_b128 v[156:159], v222 offset:52224
	ds_read_b128 v[160:163], v222 offset:53248
	ds_read_b128 v[164:167], v222 offset:54272
	ds_read_b128 v[190:193], v222 offset:55296
	ds_read_b128 v[194:197], v222 offset:56320
	global_load_lds_dwordx4 v[230:231], off
	v_lshl_add_u64 v[230:231], v[236:237], 0, s[20:21]
	s_mov_b32 m0, s97
	s_nop 0
	global_load_lds_dwordx4 v[230:231], off
	s_barrier
	s_waitcnt lgkmcnt(0)


	v_mfma_f32_16x16x32_bf16 v[60:63], v[128:131], v[144:147], v[60:63]
	v_mfma_f32_16x16x32_bf16 v[52:55], v[136:139], v[144:147], v[52:55]
	v_mfma_f32_16x16x32_bf16 v[44:47], v[128:131], v[152:155], v[44:47]
	v_mfma_f32_16x16x32_bf16 v[36:39], v[136:139], v[152:155], v[36:39]
	v_mfma_f32_16x16x32_bf16 v[28:31], v[128:131], v[160:163], v[28:31]
	v_mfma_f32_16x16x32_bf16 v[20:23], v[136:139], v[160:163], v[20:23]
	v_mfma_f32_16x16x32_bf16 v[12:15], v[128:131], v[190:193], v[12:15]
	v_mfma_f32_16x16x32_bf16 v[4:7], v[136:139], v[190:193], v[4:7]
	v_mfma_f32_16x16x32_bf16 v[60:63], v[132:135], v[148:151], v[60:63]
	v_mfma_f32_16x16x32_bf16 v[52:55], v[140:143], v[148:151], v[52:55]
	v_mfma_f32_16x16x32_bf16 v[44:47], v[132:135], v[156:159], v[44:47]
	v_mfma_f32_16x16x32_bf16 v[36:39], v[140:143], v[156:159], v[36:39]
	v_mfma_f32_16x16x32_bf16 v[28:31], v[132:135], v[164:167], v[28:31]
	v_mfma_f32_16x16x32_bf16 v[20:23], v[140:143], v[164:167], v[20:23]
	v_mfma_f32_16x16x32_bf16 v[12:15], v[132:135], v[194:197], v[12:15]
	v_mfma_f32_16x16x32_bf16 v[4:7], v[140:143], v[194:197], v[4:7]

	s_barrier
	s_add_u32 s8, s8, 0x80080
	s_addc_u32 s9, s9, 0
	s_add_i32 s10, s10, s57
	v_lshl_add_u64 v[128:129], s[8:9], 0, v[172:173]
	s_mov_b32 m0, s10
	s_nop 0
	global_load_lds_dwordx4 v[128:129], off
	v_lshl_add_u64 v[128:129], s[8:9], 0, v[174:175]
	s_add_i32 m0, s10, 0x2000
	s_nop 0
	global_load_lds_dwordx4 v[128:129], off
	s_waitcnt vmcnt(6)
	s_barrier

	v_mfma_f32_16x16x32_bf16 v[56:59], v[198:201], v[144:147], v[56:59]
	v_mfma_f32_16x16x32_bf16 v[48:51], v[206:209], v[144:147], v[48:51]
	v_mfma_f32_16x16x32_bf16 v[40:43], v[198:201], v[152:155], v[40:43]
	v_mfma_f32_16x16x32_bf16 v[32:35], v[206:209], v[152:155], v[32:35]
	v_mfma_f32_16x16x32_bf16 v[24:27], v[198:201], v[160:163], v[24:27]
	v_mfma_f32_16x16x32_bf16 v[16:19], v[206:209], v[160:163], v[16:19]
	v_mfma_f32_16x16x32_bf16 v[8:11], v[198:201], v[190:193], v[8:11]
	v_mfma_f32_16x16x32_bf16 v[0:3], v[206:209], v[190:193], v[0:3]
	v_mfma_f32_16x16x32_bf16 v[56:59], v[202:205], v[148:151], v[56:59]
	v_mfma_f32_16x16x32_bf16 v[48:51], v[226:229], v[148:151], v[48:51]
	v_mfma_f32_16x16x32_bf16 v[40:43], v[202:205], v[156:159], v[40:43]
	v_mfma_f32_16x16x32_bf16 v[32:35], v[226:229], v[156:159], v[32:35]
	v_mfma_f32_16x16x32_bf16 v[24:27], v[202:205], v[164:167], v[24:27]
	v_mfma_f32_16x16x32_bf16 v[16:19], v[226:229], v[164:167], v[16:19]
	v_mfma_f32_16x16x32_bf16 v[8:11], v[202:205], v[194:197], v[8:11]
	v_mfma_f32_16x16x32_bf16 v[0:3], v[226:229], v[194:197], v[0:3]

	s_add_i32 s53, s53, 2
	s_add_u32 s6, s6, 0x100
	s_addc_u32 s7, s7, 0
	s_add_u32 s51, s51, 0x100
	s_addc_u32 s52, s52, 0
	s_cmp_gt_u32 s53, 29
	s_barrier
	s_cbranch_scc0 .LBB0_118
	v_mov_b32_e32 v142, v210
	v_mov_b32_e32 v143, v169
	s_lshl_b32 s33, s4, 8
	s_add_i32 s33, s33, s34
	v_lshl_add_u32 v133, v142, 4, v143
	v_ashrrev_i32_e32 v198, 2, v133
	v_and_b32_e32 v192, 3, v143
	v_and_b32_e32 v128, -4, v133
	s_cmp_gt_i32 s4, 30
	v_lshl_add_u32 v226, v192, 6, v128
	v_add_u32_e32 v190, s33, v198
	s_cselect_b64 s[52:53], -1, 0
	s_cmp_gt_i32 s50, 8
	s_mov_b64 s[4:5], -1
	s_cbranch_scc0 .LBB0_419
	s_cmp_lg_u32 s50, 9
	s_cbranch_scc0 .LBB0_225
	s_cmp_gt_u32 s50, 25
	s_cbranch_scc0 .LBB0_127
	v_mul_f32_e32 v130, 0xbfb8aa3b, v120
	v_mul_f32_e32 v131, 0xbfb8aa3b, v121
	v_mul_f32_e32 v132, 0xbfb8aa3b, v122
	v_mul_f32_e32 v134, 0xbfb8aa3b, v123
	v_mul_f32_e32 v135, 0xbfb8aa3b, v112
	v_mul_f32_e32 v136, 0xbfb8aa3b, v113
	v_mul_f32_e32 v137, 0xbfb8aa3b, v114
	v_mul_f32_e32 v138, 0xbfb8aa3b, v115
	v_mul_f32_e32 v139, 0xbfb8aa3b, v104
	v_mul_f32_e32 v140, 0xbfb8aa3b, v105
	v_mul_f32_e32 v141, 0xbfb8aa3b, v106
	v_mul_f32_e32 v144, 0xbfb8aa3b, v107
	v_mul_f32_e32 v145, 0xbfb8aa3b, v96
	v_mul_f32_e32 v146, 0xbfb8aa3b, v97
	v_mul_f32_e32 v147, 0xbfb8aa3b, v98
	v_mul_f32_e32 v148, 0xbfb8aa3b, v99
	v_mul_f32_e32 v149, 0xbfb8aa3b, v88
	v_mul_f32_e32 v150, 0xbfb8aa3b, v89
	v_mul_f32_e32 v151, 0xbfb8aa3b, v90
	v_mul_f32_e32 v152, 0xbfb8aa3b, v91
	v_mul_f32_e32 v153, 0xbfb8aa3b, v80
	v_mul_f32_e32 v154, 0xbfb8aa3b, v81
	v_mul_f32_e32 v155, 0xbfb8aa3b, v82
	v_mul_f32_e32 v180, 0xbfb8aa3b, v83
	v_mul_f32_e32 v206, 0xbfb8aa3b, v72
	v_mul_f32_e32 v207, 0xbfb8aa3b, v73
	v_mul_f32_e32 v208, 0xbfb8aa3b, v74
	v_mul_f32_e32 v209, 0xbfb8aa3b, v75
	v_mul_f32_e32 v227, 0xbfb8aa3b, v64
	v_mul_f32_e32 v228, 0xbfb8aa3b, v65
	v_mul_f32_e32 v229, 0xbfb8aa3b, v66
	v_mul_f32_e32 v230, 0xbfb8aa3b, v67
	v_exp_f32_e32 v205, v130
	v_exp_f32_e32 v204, v131
	v_exp_f32_e32 v203, v132
	v_exp_f32_e32 v202, v134
	v_exp_f32_e32 v200, v135
	v_exp_f32_e32 v199, v136
	v_exp_f32_e32 v197, v137
	v_exp_f32_e32 v196, v138
	v_exp_f32_e32 v195, v139
	v_exp_f32_e32 v194, v140
	v_exp_f32_e32 v193, v141
	v_exp_f32_e32 v167, v144
	v_exp_f32_e32 v166, v145
	v_exp_f32_e32 v165, v146
	v_exp_f32_e32 v164, v147
	v_exp_f32_e32 v163, v148
	v_exp_f32_e32 v162, v149
	v_exp_f32_e32 v161, v150
	v_exp_f32_e32 v160, v151
	v_exp_f32_e32 v159, v152
	v_exp_f32_e32 v158, v153
	v_exp_f32_e32 v157, v154
	v_exp_f32_e32 v156, v155
	v_exp_f32_e32 v155, v180
	v_exp_f32_e32 v154, v206
	v_exp_f32_e32 v153, v207
	v_exp_f32_e32 v152, v208
	v_exp_f32_e32 v151, v209
	v_exp_f32_e32 v150, v227
	v_exp_f32_e32 v149, v228
	v_exp_f32_e32 v148, v229
	v_exp_f32_e32 v147, v230
	v_ashrrev_i32_e32 v191, 31, v190
	s_cmp_lt_u32 s50, 42
	v_lshlrev_b32_e32 v201, 2, v192
	v_lshlrev_b64 v[128:129], 12, v[190:191]
	v_mul_f32_e32 v146, 0xbfb8aa3b, v56
	v_mul_f32_e32 v145, 0xbfb8aa3b, v57
	v_mul_f32_e32 v144, 0xbfb8aa3b, v58
	v_mul_f32_e32 v141, 0xbfb8aa3b, v59
	v_mul_f32_e32 v140, 0xbfb8aa3b, v48
	v_mul_f32_e32 v139, 0xbfb8aa3b, v49
	v_mul_f32_e32 v138, 0xbfb8aa3b, v50
	v_mul_f32_e32 v137, 0xbfb8aa3b, v51
	v_mul_f32_e32 v136, 0xbfb8aa3b, v40
	v_mul_f32_e32 v135, 0xbfb8aa3b, v41
	v_mul_f32_e32 v134, 0xbfb8aa3b, v42
	v_mul_f32_e32 v132, 0xbfb8aa3b, v43
	s_cbranch_scc1 .LBB0_124
	v_mul_f32_e32 v130, 0xbfb8aa3b, v124
	v_mul_f32_e32 v131, 0xbfb8aa3b, v125
	v_mul_f32_e32 v206, 0xbfb8aa3b, v126
	v_mul_f32_e32 v207, 0xbfb8aa3b, v127
	v_exp_f32_e32 v130, v130
	v_exp_f32_e32 v131, v131
	v_exp_f32_e32 v206, v206
	v_exp_f32_e32 v207, v207
	v_add_f32_e32 v130, 1.0, v130
	v_add_f32_e32 v131, 1.0, v131
	v_add_f32_e32 v206, 1.0, v206
	v_add_f32_e32 v207, 1.0, v207
	v_rcp_f32_e32 v130, v130
	v_rcp_f32_e32 v131, v131
	v_rcp_f32_e32 v206, v206
	v_rcp_f32_e32 v207, v207
	s_lshl_b32 s4, s50, 8
	v_cvt_pk_bf16_f32 v130, v130, v131
	s_add_i32 s4, s28, s4
	v_cvt_pk_bf16_f32 v131, v206, v207
	ds_bpermute_b32 v206, v226, v130
	ds_bpermute_b32 v207, v226, v131
	v_or_b32_e32 v180, s4, v201
	v_lshl_add_u64 v[130:131], s[40:41], 0, v[128:129]
	v_lshlrev_b64 v[208:209], 1, v[180:181]
	v_lshl_add_u64 v[130:131], v[130:131], 0, v[208:209]
	s_waitcnt lgkmcnt(0)
	global_store_dwordx2 v[130:131], v[206:207], off
	v_mul_f32_e32 v180, 0xbfb8aa3b, v116
	v_mul_f32_e32 v206, 0xbfb8aa3b, v117
	v_mul_f32_e32 v207, 0xbfb8aa3b, v118
	v_mul_f32_e32 v208, 0xbfb8aa3b, v119
	v_exp_f32_e32 v180, v180
	v_exp_f32_e32 v206, v206
	v_exp_f32_e32 v207, v207
	v_exp_f32_e32 v208, v208
	v_add_f32_e32 v180, 1.0, v180
	v_add_f32_e32 v206, 1.0, v206
	v_add_f32_e32 v207, 1.0, v207
	v_add_f32_e32 v208, 1.0, v208
	v_rcp_f32_e32 v180, v180
	v_rcp_f32_e32 v206, v206
	v_rcp_f32_e32 v207, v207
	v_rcp_f32_e32 v208, v208
	s_mov_b64 s[4:5], 0x10000
	v_cvt_pk_bf16_f32 v180, v180, v206
	ds_bpermute_b32 v206, v226, v180
	v_cvt_pk_bf16_f32 v207, v207, v208
	ds_bpermute_b32 v207, v226, v207
	v_add_f32_e32 v180, 1.0, v205
	v_add_f32_e32 v208, 1.0, v202
	v_rcp_f32_e32 v180, v180
	v_rcp_f32_e32 v208, v208
	s_waitcnt lgkmcnt(0)
	global_store_dwordx2 v[130:131], v[206:207], off offset:32
	v_add_f32_e32 v206, 1.0, v204
	v_add_f32_e32 v207, 1.0, v203
	v_rcp_f32_e32 v206, v206
	v_rcp_f32_e32 v207, v207
	v_mul_f32_e32 v227, 0xbfb8aa3b, v103
	v_exp_f32_e32 v227, v227
	v_cvt_pk_bf16_f32 v180, v180, v206
	v_cvt_pk_bf16_f32 v207, v207, v208
	ds_bpermute_b32 v206, v226, v180
	ds_bpermute_b32 v207, v226, v207
	v_add_f32_e32 v180, 1.0, v200
	v_add_f32_e32 v208, 1.0, v196
	v_rcp_f32_e32 v180, v180
	v_rcp_f32_e32 v208, v208
	s_waitcnt lgkmcnt(0)
	global_store_dwordx2 v[130:131], v[206:207], off offset:256
	v_add_f32_e32 v206, 1.0, v199
	v_add_f32_e32 v207, 1.0, v197
	v_rcp_f32_e32 v206, v206
	v_rcp_f32_e32 v207, v207
	v_add_f32_e32 v227, 1.0, v227
	v_rcp_f32_e32 v227, v227
	v_cvt_pk_bf16_f32 v180, v180, v206
	v_cvt_pk_bf16_f32 v207, v207, v208
	ds_bpermute_b32 v206, v226, v180
	ds_bpermute_b32 v207, v226, v207
	v_mul_f32_e32 v180, 0xbfb8aa3b, v108
	v_mul_f32_e32 v208, 0xbfb8aa3b, v111
	v_exp_f32_e32 v180, v180
	v_exp_f32_e32 v208, v208
	s_waitcnt lgkmcnt(0)
	global_store_dwordx2 v[130:131], v[206:207], off offset:288
	v_mul_f32_e32 v206, 0xbfb8aa3b, v109
	v_mul_f32_e32 v207, 0xbfb8aa3b, v110
	v_exp_f32_e32 v206, v206
	v_exp_f32_e32 v207, v207
	v_add_f32_e32 v180, 1.0, v180
	v_add_f32_e32 v208, 1.0, v208
	v_add_f32_e32 v206, 1.0, v206
	v_add_f32_e32 v207, 1.0, v207
	v_rcp_f32_e32 v180, v180
	v_rcp_f32_e32 v206, v206
	v_rcp_f32_e32 v207, v207
	v_rcp_f32_e32 v208, v208
	v_cvt_pk_bf16_f32 v180, v180, v206
	ds_bpermute_b32 v206, v226, v180
	v_cvt_pk_bf16_f32 v207, v207, v208
	ds_bpermute_b32 v207, v226, v207
	v_lshl_add_u64 v[208:209], v[130:131], 0, s[4:5]
	s_mov_b32 s4, 0x10000
	v_add_co_u32_e32 v228, vcc, s4, v130
	v_mul_f32_e32 v180, 0xbfb8aa3b, v100
	s_nop 0
	v_addc_co_u32_e32 v229, vcc, 0, v131, vcc
	s_waitcnt lgkmcnt(0)
	global_store_dwordx2 v[228:229], v[206:207], off
	v_mul_f32_e32 v206, 0xbfb8aa3b, v101
	v_mul_f32_e32 v207, 0xbfb8aa3b, v102
	v_exp_f32_e32 v180, v180
	v_exp_f32_e32 v206, v206
	v_exp_f32_e32 v207, v207
	s_mov_b64 s[4:5], 0x20000
	v_add_f32_e32 v180, 1.0, v180
	v_add_f32_e32 v206, 1.0, v206
	v_add_f32_e32 v207, 1.0, v207
	v_rcp_f32_e32 v180, v180
	v_rcp_f32_e32 v206, v206
	v_rcp_f32_e32 v207, v207
	v_cvt_pk_bf16_f32 v180, v180, v206
	v_cvt_pk_bf16_f32 v207, v207, v227
	ds_bpermute_b32 v206, v226, v180
	ds_bpermute_b32 v207, v226, v207
	v_add_f32_e32 v180, 1.0, v195
	v_add_f32_e32 v227, 1.0, v167
	v_rcp_f32_e32 v180, v180
	v_rcp_f32_e32 v227, v227
	s_waitcnt lgkmcnt(0)
	global_store_dwordx2 v[208:209], v[206:207], off offset:32
	v_add_f32_e32 v206, 1.0, v194
	v_add_f32_e32 v207, 1.0, v193
	v_rcp_f32_e32 v206, v206
	v_rcp_f32_e32 v207, v207
	v_cvt_pk_bf16_f32 v180, v180, v206
	v_cvt_pk_bf16_f32 v207, v207, v227
	ds_bpermute_b32 v206, v226, v180
	ds_bpermute_b32 v207, v226, v207
	v_add_f32_e32 v180, 1.0, v166
	v_add_f32_e32 v227, 1.0, v163
	v_rcp_f32_e32 v180, v180
	v_rcp_f32_e32 v227, v227
	s_waitcnt lgkmcnt(0)
	global_store_dwordx2 v[208:209], v[206:207], off offset:256
	v_add_f32_e32 v206, 1.0, v165
	v_add_f32_e32 v207, 1.0, v164
	v_rcp_f32_e32 v206, v206
	v_rcp_f32_e32 v207, v207
	v_cvt_pk_bf16_f32 v180, v180, v206
	v_cvt_pk_bf16_f32 v207, v207, v227
	ds_bpermute_b32 v206, v226, v180
	ds_bpermute_b32 v207, v226, v207
	v_mul_f32_e32 v180, 0xbfb8aa3b, v92
	v_exp_f32_e32 v180, v180
	v_mul_f32_e32 v227, 0xbfb8aa3b, v87
	v_exp_f32_e32 v227, v227
	s_waitcnt lgkmcnt(0)
	global_store_dwordx2 v[208:209], v[206:207], off offset:288
	v_mul_f32_e32 v206, 0xbfb8aa3b, v93
	v_mul_f32_e32 v207, 0xbfb8aa3b, v94
	v_mul_f32_e32 v208, 0xbfb8aa3b, v95
	v_exp_f32_e32 v206, v206
	v_exp_f32_e32 v207, v207
	v_exp_f32_e32 v208, v208
	v_add_f32_e32 v180, 1.0, v180
	v_add_f32_e32 v206, 1.0, v206
	v_add_f32_e32 v207, 1.0, v207
	v_add_f32_e32 v208, 1.0, v208
	v_rcp_f32_e32 v180, v180
	v_rcp_f32_e32 v206, v206
	v_rcp_f32_e32 v207, v207
	v_rcp_f32_e32 v208, v208
	v_add_f32_e32 v227, 1.0, v227
	v_cvt_pk_bf16_f32 v180, v180, v206
	ds_bpermute_b32 v206, v226, v180
	v_cvt_pk_bf16_f32 v207, v207, v208
	ds_bpermute_b32 v207, v226, v207
	v_lshl_add_u64 v[208:209], v[130:131], 0, s[4:5]
	s_mov_b32 s4, 0x20000
	v_add_co_u32_e32 v228, vcc, s4, v130
	v_mul_f32_e32 v180, 0xbfb8aa3b, v84
	s_nop 0
	v_addc_co_u32_e32 v229, vcc, 0, v131, vcc
	s_waitcnt lgkmcnt(0)
	global_store_dwordx2 v[228:229], v[206:207], off
	v_mul_f32_e32 v206, 0xbfb8aa3b, v85
	v_mul_f32_e32 v207, 0xbfb8aa3b, v86
	v_exp_f32_e32 v180, v180
	v_exp_f32_e32 v206, v206
	v_exp_f32_e32 v207, v207
	v_rcp_f32_e32 v227, v227
	v_add_f32_e32 v180, 1.0, v180
	v_add_f32_e32 v206, 1.0, v206
	v_add_f32_e32 v207, 1.0, v207
	v_rcp_f32_e32 v180, v180
	v_rcp_f32_e32 v206, v206
	v_rcp_f32_e32 v207, v207
	s_mov_b64 s[4:5], 0x30000
	v_cvt_pk_bf16_f32 v180, v180, v206
	v_cvt_pk_bf16_f32 v207, v207, v227
	ds_bpermute_b32 v206, v226, v180
	ds_bpermute_b32 v207, v226, v207
	v_add_f32_e32 v180, 1.0, v162
	v_add_f32_e32 v227, 1.0, v159
	v_rcp_f32_e32 v180, v180
	v_rcp_f32_e32 v227, v227
	s_waitcnt lgkmcnt(0)
	global_store_dwordx2 v[208:209], v[206:207], off offset:32
	v_add_f32_e32 v206, 1.0, v161
	v_add_f32_e32 v207, 1.0, v160
	v_rcp_f32_e32 v206, v206
	v_rcp_f32_e32 v207, v207
	v_cvt_pk_bf16_f32 v180, v180, v206
	v_cvt_pk_bf16_f32 v207, v207, v227
	ds_bpermute_b32 v206, v226, v180
	ds_bpermute_b32 v207, v226, v207
	v_add_f32_e32 v180, 1.0, v158
	v_add_f32_e32 v227, 1.0, v155
	v_rcp_f32_e32 v180, v180
	v_rcp_f32_e32 v227, v227
	s_waitcnt lgkmcnt(0)
	global_store_dwordx2 v[208:209], v[206:207], off offset:256
	v_add_f32_e32 v206, 1.0, v157
	v_add_f32_e32 v207, 1.0, v156
	v_rcp_f32_e32 v206, v206
	v_rcp_f32_e32 v207, v207
	v_cvt_pk_bf16_f32 v180, v180, v206
	v_cvt_pk_bf16_f32 v207, v207, v227
	ds_bpermute_b32 v206, v226, v180
	ds_bpermute_b32 v207, v226, v207
	v_mul_f32_e32 v180, 0xbfb8aa3b, v76
	v_exp_f32_e32 v180, v180
	v_mul_f32_e32 v227, 0xbfb8aa3b, v71
	v_exp_f32_e32 v227, v227
	s_waitcnt lgkmcnt(0)
	global_store_dwordx2 v[208:209], v[206:207], off offset:288
	v_mul_f32_e32 v206, 0xbfb8aa3b, v77
	v_mul_f32_e32 v207, 0xbfb8aa3b, v78
	v_mul_f32_e32 v208, 0xbfb8aa3b, v79
	v_exp_f32_e32 v206, v206
	v_exp_f32_e32 v207, v207
	v_exp_f32_e32 v208, v208
	v_add_f32_e32 v180, 1.0, v180
	v_add_f32_e32 v206, 1.0, v206
	v_add_f32_e32 v207, 1.0, v207
	v_add_f32_e32 v208, 1.0, v208
	v_rcp_f32_e32 v180, v180
	v_rcp_f32_e32 v206, v206
	v_rcp_f32_e32 v207, v207
	v_rcp_f32_e32 v208, v208
	v_add_f32_e32 v227, 1.0, v227
	v_cvt_pk_bf16_f32 v180, v180, v206
	ds_bpermute_b32 v206, v226, v180
	v_cvt_pk_bf16_f32 v207, v207, v208
	ds_bpermute_b32 v207, v226, v207
	v_lshl_add_u64 v[208:209], v[130:131], 0, s[4:5]
	s_mov_b32 s4, 0x30000
	v_add_co_u32_e32 v228, vcc, s4, v130
	v_mul_f32_e32 v180, 0xbfb8aa3b, v68
	s_nop 0
	v_addc_co_u32_e32 v229, vcc, 0, v131, vcc
	s_waitcnt lgkmcnt(0)
	global_store_dwordx2 v[228:229], v[206:207], off
	v_mul_f32_e32 v206, 0xbfb8aa3b, v69
	v_mul_f32_e32 v207, 0xbfb8aa3b, v70
	v_exp_f32_e32 v180, v180
	v_exp_f32_e32 v206, v206
	v_exp_f32_e32 v207, v207
	v_rcp_f32_e32 v227, v227
	v_add_f32_e32 v180, 1.0, v180
	v_add_f32_e32 v206, 1.0, v206
	v_add_f32_e32 v207, 1.0, v207
	v_rcp_f32_e32 v180, v180
	v_rcp_f32_e32 v206, v206
	v_rcp_f32_e32 v207, v207
	s_mov_b64 s[4:5], 0x80000
	v_cvt_pk_bf16_f32 v180, v180, v206
	v_cvt_pk_bf16_f32 v207, v207, v227
	ds_bpermute_b32 v206, v226, v180
	ds_bpermute_b32 v207, v226, v207
	v_add_f32_e32 v180, 1.0, v154
	v_add_f32_e32 v227, 1.0, v151
	v_rcp_f32_e32 v180, v180
	v_rcp_f32_e32 v227, v227
	s_waitcnt lgkmcnt(0)
	global_store_dwordx2 v[208:209], v[206:207], off offset:32
	v_add_f32_e32 v206, 1.0, v153
	v_add_f32_e32 v207, 1.0, v152
	v_rcp_f32_e32 v206, v206
	v_rcp_f32_e32 v207, v207
	v_cvt_pk_bf16_f32 v180, v180, v206
	v_cvt_pk_bf16_f32 v207, v207, v227
	ds_bpermute_b32 v206, v226, v180
	ds_bpermute_b32 v207, v226, v207
	v_add_f32_e32 v180, 1.0, v150
	v_add_f32_e32 v227, 1.0, v147
	v_rcp_f32_e32 v180, v180
	v_rcp_f32_e32 v227, v227
	s_waitcnt lgkmcnt(0)
	global_store_dwordx2 v[208:209], v[206:207], off offset:256
	v_add_f32_e32 v206, 1.0, v149
	v_add_f32_e32 v207, 1.0, v148
	v_rcp_f32_e32 v206, v206
	v_rcp_f32_e32 v207, v207
	v_cvt_pk_bf16_f32 v180, v180, v206
	v_cvt_pk_bf16_f32 v207, v207, v227
	ds_bpermute_b32 v206, v226, v180
	ds_bpermute_b32 v207, v226, v207
	v_mul_f32_e32 v180, 0xbfb8aa3b, v60
	v_exp_f32_e32 v180, v180
	v_mul_f32_e32 v227, 0xbfb8aa3b, v55
	v_exp_f32_e32 v227, v227
	s_waitcnt lgkmcnt(0)
	global_store_dwordx2 v[208:209], v[206:207], off offset:288
	v_mul_f32_e32 v206, 0xbfb8aa3b, v61
	v_mul_f32_e32 v207, 0xbfb8aa3b, v62
	v_mul_f32_e32 v208, 0xbfb8aa3b, v63
	v_exp_f32_e32 v206, v206
	v_exp_f32_e32 v207, v207
	v_exp_f32_e32 v208, v208
	v_add_f32_e32 v180, 1.0, v180
	v_add_f32_e32 v206, 1.0, v206
	v_add_f32_e32 v207, 1.0, v207
	v_add_f32_e32 v208, 1.0, v208
	v_rcp_f32_e32 v180, v180
	v_rcp_f32_e32 v206, v206
	v_rcp_f32_e32 v207, v207
	v_rcp_f32_e32 v208, v208
	v_add_f32_e32 v227, 1.0, v227
	v_cvt_pk_bf16_f32 v180, v180, v206
	ds_bpermute_b32 v206, v226, v180
	v_cvt_pk_bf16_f32 v207, v207, v208
	ds_bpermute_b32 v207, v226, v207
	v_lshl_add_u64 v[208:209], v[130:131], 0, s[4:5]
	s_mov_b32 s4, 0x80000
	v_add_co_u32_e32 v228, vcc, s4, v130
	v_mul_f32_e32 v180, 0xbfb8aa3b, v52
	s_nop 0
	v_addc_co_u32_e32 v229, vcc, 0, v131, vcc
	s_waitcnt lgkmcnt(0)
	global_store_dwordx2 v[228:229], v[206:207], off
	v_mul_f32_e32 v206, 0xbfb8aa3b, v53
	v_mul_f32_e32 v207, 0xbfb8aa3b, v54
	v_exp_f32_e32 v180, v180
	v_exp_f32_e32 v206, v206
	v_exp_f32_e32 v207, v207
	v_rcp_f32_e32 v227, v227
	v_add_f32_e32 v180, 1.0, v180
	v_add_f32_e32 v206, 1.0, v206
	v_add_f32_e32 v207, 1.0, v207
	v_rcp_f32_e32 v180, v180
	v_rcp_f32_e32 v206, v206
	v_rcp_f32_e32 v207, v207
	s_mov_b64 s[4:5], 0x90000
	v_cvt_pk_bf16_f32 v180, v180, v206
	v_cvt_pk_bf16_f32 v207, v207, v227
	ds_bpermute_b32 v206, v226, v180
	ds_bpermute_b32 v207, v226, v207
	v_exp_f32_e32 v180, v146
	v_exp_f32_e32 v227, v141
	s_waitcnt lgkmcnt(0)
	global_store_dwordx2 v[208:209], v[206:207], off offset:32
	v_exp_f32_e32 v206, v145
	v_exp_f32_e32 v207, v144
	v_add_f32_e32 v180, 1.0, v180
	v_add_f32_e32 v227, 1.0, v227
	v_add_f32_e32 v206, 1.0, v206
	v_add_f32_e32 v207, 1.0, v207
	v_rcp_f32_e32 v180, v180
	v_rcp_f32_e32 v206, v206
	v_rcp_f32_e32 v207, v207
	v_rcp_f32_e32 v227, v227
	v_cvt_pk_bf16_f32 v180, v180, v206
	ds_bpermute_b32 v206, v226, v180
	v_cvt_pk_bf16_f32 v207, v207, v227
	ds_bpermute_b32 v207, v226, v207
	v_exp_f32_e32 v180, v140
	v_exp_f32_e32 v227, v137
	s_waitcnt lgkmcnt(0)
	global_store_dwordx2 v[208:209], v[206:207], off offset:256
	v_exp_f32_e32 v206, v139
	v_exp_f32_e32 v207, v138
	v_add_f32_e32 v180, 1.0, v180
	v_add_f32_e32 v227, 1.0, v227
	v_add_f32_e32 v206, 1.0, v206
	v_add_f32_e32 v207, 1.0, v207
	v_rcp_f32_e32 v180, v180
	v_rcp_f32_e32 v206, v206
	v_rcp_f32_e32 v207, v207
	v_rcp_f32_e32 v227, v227
	v_cvt_pk_bf16_f32 v180, v180, v206
	ds_bpermute_b32 v206, v226, v180
	v_cvt_pk_bf16_f32 v207, v207, v227
	ds_bpermute_b32 v207, v226, v207
	v_mul_f32_e32 v180, 0xbfb8aa3b, v44
	v_exp_f32_e32 v180, v180
	v_mul_f32_e32 v227, 0xbfb8aa3b, v39
	v_exp_f32_e32 v227, v227
	s_waitcnt lgkmcnt(0)
	global_store_dwordx2 v[208:209], v[206:207], off offset:288
	v_mul_f32_e32 v206, 0xbfb8aa3b, v45
	v_mul_f32_e32 v207, 0xbfb8aa3b, v46
	v_mul_f32_e32 v208, 0xbfb8aa3b, v47
	v_exp_f32_e32 v206, v206
	v_exp_f32_e32 v207, v207
	v_exp_f32_e32 v208, v208
	v_add_f32_e32 v180, 1.0, v180
	v_add_f32_e32 v206, 1.0, v206
	v_add_f32_e32 v207, 1.0, v207
	v_add_f32_e32 v208, 1.0, v208
	v_rcp_f32_e32 v180, v180
	v_rcp_f32_e32 v206, v206
	v_rcp_f32_e32 v207, v207
	v_rcp_f32_e32 v208, v208
	v_add_f32_e32 v227, 1.0, v227
	v_cvt_pk_bf16_f32 v180, v180, v206
	ds_bpermute_b32 v206, v226, v180
	v_cvt_pk_bf16_f32 v207, v207, v208
	ds_bpermute_b32 v207, v226, v207
	v_lshl_add_u64 v[208:209], v[130:131], 0, s[4:5]
	s_mov_b32 s4, 0x90000
	v_add_co_u32_e32 v228, vcc, s4, v130
	v_mul_f32_e32 v180, 0xbfb8aa3b, v36
	s_nop 0
	v_addc_co_u32_e32 v229, vcc, 0, v131, vcc
	s_waitcnt lgkmcnt(0)
	global_store_dwordx2 v[228:229], v[206:207], off
	v_mul_f32_e32 v206, 0xbfb8aa3b, v37
	v_mul_f32_e32 v207, 0xbfb8aa3b, v38
	v_exp_f32_e32 v180, v180
	v_exp_f32_e32 v206, v206
	v_exp_f32_e32 v207, v207
	v_rcp_f32_e32 v227, v227
	v_add_f32_e32 v180, 1.0, v180
	v_add_f32_e32 v206, 1.0, v206
	v_add_f32_e32 v207, 1.0, v207
	v_rcp_f32_e32 v180, v180
	v_rcp_f32_e32 v206, v206
	v_rcp_f32_e32 v207, v207
	s_mov_b64 s[4:5], 0xa0000
	v_cvt_pk_bf16_f32 v180, v180, v206
	v_cvt_pk_bf16_f32 v207, v207, v227
	ds_bpermute_b32 v206, v226, v180
	ds_bpermute_b32 v207, v226, v207
	v_exp_f32_e32 v180, v136
	v_exp_f32_e32 v227, v132
	s_waitcnt lgkmcnt(0)
	global_store_dwordx2 v[208:209], v[206:207], off offset:32
	v_exp_f32_e32 v206, v135
	v_exp_f32_e32 v207, v134
	v_add_f32_e32 v180, 1.0, v180
	v_add_f32_e32 v227, 1.0, v227
	v_add_f32_e32 v206, 1.0, v206
	v_add_f32_e32 v207, 1.0, v207
	v_rcp_f32_e32 v180, v180
	v_rcp_f32_e32 v206, v206
	v_rcp_f32_e32 v207, v207
	v_rcp_f32_e32 v227, v227
	v_cvt_pk_bf16_f32 v180, v180, v206
	ds_bpermute_b32 v206, v226, v180
	v_cvt_pk_bf16_f32 v207, v207, v227
	ds_bpermute_b32 v207, v226, v207
	v_mul_f32_e32 v180, 0xbfb8aa3b, v32
	v_mul_f32_e32 v227, 0xbfb8aa3b, v35
	v_exp_f32_e32 v180, v180
	v_exp_f32_e32 v227, v227
	s_waitcnt lgkmcnt(0)
	global_store_dwordx2 v[208:209], v[206:207], off offset:256
	v_mul_f32_e32 v206, 0xbfb8aa3b, v33
	v_mul_f32_e32 v207, 0xbfb8aa3b, v34
	v_exp_f32_e32 v206, v206
	v_exp_f32_e32 v207, v207
	v_add_f32_e32 v180, 1.0, v180
	v_add_f32_e32 v227, 1.0, v227
	v_add_f32_e32 v206, 1.0, v206
	v_add_f32_e32 v207, 1.0, v207
	v_rcp_f32_e32 v180, v180
	v_rcp_f32_e32 v206, v206
	v_rcp_f32_e32 v207, v207
	v_rcp_f32_e32 v227, v227
	v_cvt_pk_bf16_f32 v180, v180, v206
	ds_bpermute_b32 v206, v226, v180
	v_cvt_pk_bf16_f32 v207, v207, v227
	ds_bpermute_b32 v207, v226, v207
	v_mul_f32_e32 v180, 0xbfb8aa3b, v28
	v_exp_f32_e32 v180, v180
	v_mul_f32_e32 v227, 0xbfb8aa3b, v23
	v_exp_f32_e32 v227, v227
	s_waitcnt lgkmcnt(0)
	global_store_dwordx2 v[208:209], v[206:207], off offset:288
	v_mul_f32_e32 v206, 0xbfb8aa3b, v29
	v_mul_f32_e32 v207, 0xbfb8aa3b, v30
	v_mul_f32_e32 v208, 0xbfb8aa3b, v31
	v_exp_f32_e32 v206, v206
	v_exp_f32_e32 v207, v207
	v_exp_f32_e32 v208, v208
	v_add_f32_e32 v180, 1.0, v180
	v_add_f32_e32 v206, 1.0, v206
	v_add_f32_e32 v207, 1.0, v207
	v_add_f32_e32 v208, 1.0, v208
	v_rcp_f32_e32 v180, v180
	v_rcp_f32_e32 v206, v206
	v_rcp_f32_e32 v207, v207
	v_rcp_f32_e32 v208, v208
	v_add_f32_e32 v227, 1.0, v227
	v_cvt_pk_bf16_f32 v180, v180, v206
	ds_bpermute_b32 v206, v226, v180
	v_cvt_pk_bf16_f32 v207, v207, v208
	ds_bpermute_b32 v207, v226, v207
	v_lshl_add_u64 v[208:209], v[130:131], 0, s[4:5]
	s_mov_b32 s4, 0xa0000
	v_add_co_u32_e32 v228, vcc, s4, v130
	v_mul_f32_e32 v180, 0xbfb8aa3b, v20
	s_nop 0
	v_addc_co_u32_e32 v229, vcc, 0, v131, vcc
	s_waitcnt lgkmcnt(0)
	global_store_dwordx2 v[228:229], v[206:207], off
	v_mul_f32_e32 v206, 0xbfb8aa3b, v21
	v_mul_f32_e32 v207, 0xbfb8aa3b, v22
	v_exp_f32_e32 v180, v180
	v_exp_f32_e32 v206, v206
	v_exp_f32_e32 v207, v207
	v_rcp_f32_e32 v227, v227
	v_add_f32_e32 v180, 1.0, v180
	v_add_f32_e32 v206, 1.0, v206
	v_add_f32_e32 v207, 1.0, v207
	v_rcp_f32_e32 v180, v180
	v_rcp_f32_e32 v206, v206
	v_rcp_f32_e32 v207, v207
	s_mov_b64 s[4:5], 0xb0000
	v_cvt_pk_bf16_f32 v180, v180, v206
	v_cvt_pk_bf16_f32 v207, v207, v227
	ds_bpermute_b32 v206, v226, v180
	ds_bpermute_b32 v207, v226, v207
	v_mul_f32_e32 v180, 0xbfb8aa3b, v24
	v_mul_f32_e32 v227, 0xbfb8aa3b, v27
	v_exp_f32_e32 v180, v180
	v_exp_f32_e32 v227, v227
	s_waitcnt lgkmcnt(0)
	global_store_dwordx2 v[208:209], v[206:207], off offset:32
	v_mul_f32_e32 v206, 0xbfb8aa3b, v25
	v_mul_f32_e32 v207, 0xbfb8aa3b, v26
	v_exp_f32_e32 v206, v206
	v_exp_f32_e32 v207, v207
	v_add_f32_e32 v180, 1.0, v180
	v_add_f32_e32 v227, 1.0, v227
	v_add_f32_e32 v206, 1.0, v206
	v_add_f32_e32 v207, 1.0, v207
	v_rcp_f32_e32 v180, v180
	v_rcp_f32_e32 v206, v206
	v_rcp_f32_e32 v207, v207
	v_rcp_f32_e32 v227, v227
	v_cvt_pk_bf16_f32 v180, v180, v206
	ds_bpermute_b32 v206, v226, v180
	v_cvt_pk_bf16_f32 v207, v207, v227
	ds_bpermute_b32 v207, v226, v207
	v_mul_f32_e32 v180, 0xbfb8aa3b, v16
	v_mul_f32_e32 v227, 0xbfb8aa3b, v19
	v_exp_f32_e32 v180, v180
	v_exp_f32_e32 v227, v227
	s_waitcnt lgkmcnt(0)
	global_store_dwordx2 v[208:209], v[206:207], off offset:256
	v_mul_f32_e32 v206, 0xbfb8aa3b, v17
	v_mul_f32_e32 v207, 0xbfb8aa3b, v18
	v_exp_f32_e32 v206, v206
	v_exp_f32_e32 v207, v207
	v_add_f32_e32 v180, 1.0, v180
	v_add_f32_e32 v227, 1.0, v227
	v_add_f32_e32 v206, 1.0, v206
	v_add_f32_e32 v207, 1.0, v207
	v_rcp_f32_e32 v180, v180
	v_rcp_f32_e32 v206, v206
	v_rcp_f32_e32 v207, v207
	v_rcp_f32_e32 v227, v227
	v_cvt_pk_bf16_f32 v180, v180, v206
	ds_bpermute_b32 v206, v226, v180
	v_cvt_pk_bf16_f32 v207, v207, v227
	ds_bpermute_b32 v207, v226, v207
	v_mul_f32_e32 v180, 0xbfb8aa3b, v12
	v_exp_f32_e32 v180, v180
	s_waitcnt lgkmcnt(0)
	global_store_dwordx2 v[208:209], v[206:207], off offset:288
	v_mul_f32_e32 v206, 0xbfb8aa3b, v13
	v_mul_f32_e32 v207, 0xbfb8aa3b, v14
	v_mul_f32_e32 v208, 0xbfb8aa3b, v15
	v_exp_f32_e32 v206, v206
	v_exp_f32_e32 v207, v207
	v_exp_f32_e32 v208, v208
	v_add_f32_e32 v180, 1.0, v180
	v_add_f32_e32 v206, 1.0, v206
	v_add_f32_e32 v207, 1.0, v207
	v_add_f32_e32 v208, 1.0, v208
	v_rcp_f32_e32 v180, v180
	v_rcp_f32_e32 v206, v206
	v_rcp_f32_e32 v207, v207
	v_rcp_f32_e32 v208, v208
	v_cvt_pk_bf16_f32 v180, v180, v206
	ds_bpermute_b32 v206, v226, v180
	v_cvt_pk_bf16_f32 v207, v207, v208
	ds_bpermute_b32 v207, v226, v207
	v_lshl_add_u64 v[208:209], v[130:131], 0, s[4:5]
	s_mov_b32 s4, 0xb0000
	v_add_co_u32_e32 v130, vcc, s4, v130
	v_mul_f32_e32 v180, 0xbfb8aa3b, v6
	s_nop 0
	v_addc_co_u32_e32 v131, vcc, 0, v131, vcc
	s_waitcnt lgkmcnt(0)
	global_store_dwordx2 v[130:131], v[206:207], off
	v_mul_f32_e32 v130, 0xbfb8aa3b, v4
	v_mul_f32_e32 v131, 0xbfb8aa3b, v5
	v_mul_f32_e32 v206, 0xbfb8aa3b, v7
	v_exp_f32_e32 v130, v130
	v_exp_f32_e32 v131, v131
	v_exp_f32_e32 v180, v180
	v_exp_f32_e32 v206, v206
	v_add_f32_e32 v130, 1.0, v130
	v_add_f32_e32 v131, 1.0, v131
	v_add_f32_e32 v180, 1.0, v180
	v_add_f32_e32 v206, 1.0, v206
	v_rcp_f32_e32 v130, v130
	v_rcp_f32_e32 v131, v131
	v_rcp_f32_e32 v180, v180
	v_rcp_f32_e32 v206, v206
	s_mov_b64 s[4:5], 0
	v_cvt_pk_bf16_f32 v130, v130, v131
	ds_bpermute_b32 v130, v226, v130
	v_cvt_pk_bf16_f32 v131, v180, v206
	ds_bpermute_b32 v131, v226, v131
	v_mul_f32_e32 v180, 0xbfb8aa3b, v10
	v_mul_f32_e32 v206, 0xbfb8aa3b, v11
	v_exp_f32_e32 v180, v180
	v_exp_f32_e32 v206, v206
	s_waitcnt lgkmcnt(0)
	global_store_dwordx2 v[208:209], v[130:131], off offset:32
	v_mul_f32_e32 v130, 0xbfb8aa3b, v8
	v_mul_f32_e32 v131, 0xbfb8aa3b, v9
	v_exp_f32_e32 v130, v130
	v_exp_f32_e32 v131, v131
	v_add_f32_e32 v180, 1.0, v180
	v_add_f32_e32 v206, 1.0, v206
	v_add_f32_e32 v130, 1.0, v130
	v_add_f32_e32 v131, 1.0, v131
	v_rcp_f32_e32 v130, v130
	v_rcp_f32_e32 v131, v131
	v_rcp_f32_e32 v180, v180
	v_rcp_f32_e32 v206, v206
	v_cvt_pk_bf16_f32 v130, v130, v131
	ds_bpermute_b32 v130, v226, v130
	v_cvt_pk_bf16_f32 v131, v180, v206
	ds_bpermute_b32 v131, v226, v131
	v_mul_f32_e32 v180, 0xbfb8aa3b, v2
	v_mul_f32_e32 v206, 0xbfb8aa3b, v3
	v_exp_f32_e32 v180, v180
	v_exp_f32_e32 v206, v206
	s_waitcnt lgkmcnt(0)
	global_store_dwordx2 v[208:209], v[130:131], off offset:256
	v_mul_f32_e32 v130, 0xbfb8aa3b, v0
	v_mul_f32_e32 v131, 0xbfb8aa3b, v1
	v_exp_f32_e32 v130, v130
	v_exp_f32_e32 v131, v131
	v_add_f32_e32 v180, 1.0, v180
	v_add_f32_e32 v206, 1.0, v206
	v_add_f32_e32 v130, 1.0, v130
	v_add_f32_e32 v131, 1.0, v131
	v_rcp_f32_e32 v130, v130
	v_rcp_f32_e32 v131, v131
	v_rcp_f32_e32 v180, v180
	v_rcp_f32_e32 v206, v206
	v_cvt_pk_bf16_f32 v130, v130, v131
	ds_bpermute_b32 v130, v226, v130
	v_cvt_pk_bf16_f32 v131, v180, v206
	ds_bpermute_b32 v131, v226, v131
	s_waitcnt lgkmcnt(0)
	global_store_dwordx2 v[208:209], v[130:131], off offset:288

.LBB0_1024:
	s_waitcnt lgkmcnt(0)
	ds_read_b128 v[128:131], v179
	ds_read_b128 v[132:135], v179 offset:1024
	ds_read_b128 v[136:139], v179 offset:2048
	ds_read_b128 v[140:143], v179 offset:3072
	s_add_i32 s62, s36, 2
	s_add_u32 s37, s4, 0xfff80080
	s_addc_u32 s38, s5, -1
	s_cmp_eq_u32 s59, s36
	s_cselect_b32 s36, s58, s60
	s_cselect_b32 s39, s21, s38
	s_cselect_b32 s38, s25, s37
	s_cselect_b32 s37, s23, s61
	v_lshl_add_u64 v[166:167], s[4:5], 0, v[162:163]
	s_add_i32 m0, s31, 0xc000
	ds_read_b128 v[144:147], v190
	ds_read_b128 v[148:151], v190 offset:1024
	ds_read_b128 v[152:155], v190 offset:2048
	ds_read_b128 v[156:159], v190 offset:3072
	ds_read_b128 v[180:183], v190 offset:4096
	ds_read_b128 v[184:187], v190 offset:5120
	ds_read_b128 v[194:197], v190 offset:6144
	ds_read_b128 v[198:201], v190 offset:7168
	global_load_lds_dwordx4 v[166:167], off
	v_lshl_add_u64 v[166:167], s[4:5], 0, v[164:165]
	s_add_i32 m0, s31, 0xe000
	s_nop 0
	global_load_lds_dwordx4 v[166:167], off
	s_waitcnt lgkmcnt(8)
	s_barrier
	s_waitcnt lgkmcnt(0)


	v_mfma_f32_16x16x32_bf16 v[124:127], v[128:131], v[144:147], v[124:127]
	v_mfma_f32_16x16x32_bf16 v[120:123], v[136:139], v[144:147], v[120:123]
	v_mfma_f32_16x16x32_bf16 v[116:119], v[128:131], v[152:155], v[116:119]
	v_mfma_f32_16x16x32_bf16 v[104:107], v[136:139], v[152:155], v[104:107]
	v_mfma_f32_16x16x32_bf16 v[96:99], v[128:131], v[180:183], v[96:99]
	v_mfma_f32_16x16x32_bf16 v[88:91], v[136:139], v[180:183], v[88:91]
	v_mfma_f32_16x16x32_bf16 v[80:83], v[128:131], v[194:197], v[80:83]
	v_mfma_f32_16x16x32_bf16 v[72:75], v[136:139], v[194:197], v[72:75]
	v_mfma_f32_16x16x32_bf16 v[124:127], v[132:135], v[148:151], v[124:127]
	v_mfma_f32_16x16x32_bf16 v[120:123], v[140:143], v[148:151], v[120:123]
	v_mfma_f32_16x16x32_bf16 v[116:119], v[132:135], v[156:159], v[116:119]
	v_mfma_f32_16x16x32_bf16 v[104:107], v[140:143], v[156:159], v[104:107]
	v_mfma_f32_16x16x32_bf16 v[96:99], v[132:135], v[184:187], v[96:99]
	v_mfma_f32_16x16x32_bf16 v[88:91], v[140:143], v[184:187], v[88:91]
	v_mfma_f32_16x16x32_bf16 v[80:83], v[132:135], v[198:201], v[80:83]
	v_mfma_f32_16x16x32_bf16 v[72:75], v[140:143], v[198:201], v[72:75]

	s_barrier
	s_add_i32 s63, s52, s42
	v_lshl_add_u64 v[166:167], s[36:37], 0, v[172:173]
	s_mov_b32 m0, s63
	ds_read_b128 v[202:205], v191
	ds_read_b128 v[206:209], v191 offset:1024
	ds_read_b128 v[222:225], v191 offset:2048
	ds_read_b128 v[226:229], v191 offset:3072
	global_load_lds_dwordx4 v[166:167], off
	v_lshl_add_u64 v[188:189], s[36:37], 0, v[174:175]
	s_add_i32 m0, s63, 0x2000
	s_nop 0
	global_load_lds_dwordx4 v[188:189], off
	s_barrier
	s_waitcnt lgkmcnt(0)


	v_mfma_f32_16x16x32_bf16 v[112:115], v[202:205], v[144:147], v[112:115]
	v_mfma_f32_16x16x32_bf16 v[108:111], v[222:225], v[144:147], v[108:111]
	v_mfma_f32_16x16x32_bf16 v[100:103], v[202:205], v[152:155], v[100:103]
	v_mfma_f32_16x16x32_bf16 v[92:95], v[222:225], v[152:155], v[92:95]
	v_mfma_f32_16x16x32_bf16 v[84:87], v[202:205], v[180:183], v[84:87]
	v_mfma_f32_16x16x32_bf16 v[76:79], v[222:225], v[180:183], v[76:79]
	v_mfma_f32_16x16x32_bf16 v[68:71], v[202:205], v[194:197], v[68:71]
	v_mfma_f32_16x16x32_bf16 v[64:67], v[222:225], v[194:197], v[64:67]
	v_mfma_f32_16x16x32_bf16 v[112:115], v[206:209], v[148:151], v[112:115]
	v_mfma_f32_16x16x32_bf16 v[108:111], v[226:229], v[148:151], v[108:111]
	v_mfma_f32_16x16x32_bf16 v[100:103], v[206:209], v[156:159], v[100:103]
	v_mfma_f32_16x16x32_bf16 v[92:95], v[226:229], v[156:159], v[92:95]
	v_mfma_f32_16x16x32_bf16 v[84:87], v[206:209], v[184:187], v[84:87]
	v_mfma_f32_16x16x32_bf16 v[76:79], v[226:229], v[184:187], v[76:79]
	v_mfma_f32_16x16x32_bf16 v[68:71], v[206:209], v[198:201], v[68:71]
	v_mfma_f32_16x16x32_bf16 v[64:67], v[226:229], v[198:201], v[64:67]

	s_mov_b32 m0, s31
	v_lshl_add_u64 v[230:231], s[38:39], 0, v[172:173]
	s_barrier
	ds_read_b128 v[144:147], v190 offset:16384
	ds_read_b128 v[148:151], v190 offset:17408
	ds_read_b128 v[152:155], v190 offset:18432
	ds_read_b128 v[156:159], v190 offset:19456
	ds_read_b128 v[180:183], v190 offset:20480
	ds_read_b128 v[184:187], v190 offset:21504
	ds_read_b128 v[194:197], v190 offset:22528
	ds_read_b128 v[198:201], v190 offset:23552
	global_load_lds_dwordx4 v[230:231], off
	v_lshl_add_u64 v[232:233], s[38:39], 0, v[174:175]
	s_mov_b32 m0, s35
	s_nop 0
	global_load_lds_dwordx4 v[232:233], off
	s_barrier
	s_waitcnt lgkmcnt(0)


	v_mfma_f32_16x16x32_bf16 v[60:63], v[128:131], v[144:147], v[60:63]
	v_mfma_f32_16x16x32_bf16 v[56:59], v[136:139], v[144:147], v[56:59]
	v_mfma_f32_16x16x32_bf16 v[52:55], v[128:131], v[152:155], v[52:55]
	v_mfma_f32_16x16x32_bf16 v[40:43], v[136:139], v[152:155], v[40:43]
	v_mfma_f32_16x16x32_bf16 v[36:39], v[128:131], v[180:183], v[36:39]
	v_mfma_f32_16x16x32_bf16 v[24:27], v[136:139], v[180:183], v[24:27]
	v_mfma_f32_16x16x32_bf16 v[20:23], v[128:131], v[194:197], v[20:23]
	v_mfma_f32_16x16x32_bf16 v[8:11], v[136:139], v[194:197], v[8:11]
	v_mfma_f32_16x16x32_bf16 v[60:63], v[132:135], v[148:151], v[60:63]
	v_mfma_f32_16x16x32_bf16 v[56:59], v[140:143], v[148:151], v[56:59]
	v_mfma_f32_16x16x32_bf16 v[52:55], v[132:135], v[156:159], v[52:55]
	v_mfma_f32_16x16x32_bf16 v[40:43], v[140:143], v[156:159], v[40:43]
	v_mfma_f32_16x16x32_bf16 v[36:39], v[132:135], v[184:187], v[36:39]
	v_mfma_f32_16x16x32_bf16 v[24:27], v[140:143], v[184:187], v[24:27]
	v_mfma_f32_16x16x32_bf16 v[20:23], v[132:135], v[198:201], v[20:23]
	v_mfma_f32_16x16x32_bf16 v[8:11], v[140:143], v[198:201], v[8:11]

	s_barrier
	s_add_u32 s64, s36, 0x80000
	s_addc_u32 s65, s37, 0
	s_add_i32 s63, s53, s42
	v_lshl_add_u64 v[128:129], s[64:65], 0, v[172:173]
	s_mov_b32 m0, s63
	s_nop 0
	global_load_lds_dwordx4 v[128:129], off
	v_lshl_add_u64 v[128:129], s[64:65], 0, v[174:175]
	s_add_i32 m0, s63, 0x2000
	s_nop 0
	global_load_lds_dwordx4 v[128:129], off
	s_waitcnt vmcnt(6)
	s_barrier

	v_mfma_f32_16x16x32_bf16 v[48:51], v[202:205], v[144:147], v[48:51]
	v_mfma_f32_16x16x32_bf16 v[44:47], v[222:225], v[144:147], v[44:47]
	v_mfma_f32_16x16x32_bf16 v[32:35], v[202:205], v[152:155], v[32:35]
	v_mfma_f32_16x16x32_bf16 v[28:31], v[222:225], v[152:155], v[28:31]
	v_mfma_f32_16x16x32_bf16 v[16:19], v[202:205], v[180:183], v[16:19]
	v_mfma_f32_16x16x32_bf16 v[12:15], v[222:225], v[180:183], v[12:15]
	v_mfma_f32_16x16x32_bf16 v[4:7], v[202:205], v[194:197], v[4:7]
	v_mfma_f32_16x16x32_bf16 v[0:3], v[222:225], v[194:197], v[0:3]
	v_mfma_f32_16x16x32_bf16 v[48:51], v[206:209], v[148:151], v[48:51]
	v_mfma_f32_16x16x32_bf16 v[44:47], v[226:229], v[148:151], v[44:47]
	v_mfma_f32_16x16x32_bf16 v[32:35], v[206:209], v[156:159], v[32:35]
	v_mfma_f32_16x16x32_bf16 v[28:31], v[226:229], v[156:159], v[28:31]
	v_mfma_f32_16x16x32_bf16 v[16:19], v[206:209], v[184:187], v[16:19]
	v_mfma_f32_16x16x32_bf16 v[12:15], v[226:229], v[184:187], v[12:15]
	v_mfma_f32_16x16x32_bf16 v[4:7], v[206:209], v[198:201], v[4:7]
	v_mfma_f32_16x16x32_bf16 v[0:3], v[226:229], v[198:201], v[0:3]

	s_add_i32 s63, 0, 0x18000
	v_add_u32_e32 v140, s63, v177
	s_barrier
	ds_read_b128 v[128:131], v140
	ds_read_b128 v[132:135], v140 offset:1024
	ds_read_b128 v[136:139], v140 offset:2048
	ds_read_b128 v[140:143], v140 offset:3072
	s_add_u32 s38, s38, 0x80000
	s_addc_u32 s39, s39, 0
	s_mov_b32 m0, s43
	v_lshl_add_u64 v[202:203], s[38:39], 0, v[172:173]
	ds_read_b128 v[144:147], v190 offset:32768
	ds_read_b128 v[148:151], v190 offset:33792
	ds_read_b128 v[152:155], v190 offset:34816
	ds_read_b128 v[156:159], v190 offset:35840
	ds_read_b128 v[180:183], v190 offset:36864
	ds_read_b128 v[184:187], v190 offset:37888
	ds_read_b128 v[194:197], v190 offset:38912
	ds_read_b128 v[198:201], v190 offset:39936
	global_load_lds_dwordx4 v[202:203], off
	v_lshl_add_u64 v[202:203], s[38:39], 0, v[174:175]
	s_mov_b32 m0, s44
	s_nop 0
	global_load_lds_dwordx4 v[202:203], off
	s_waitcnt lgkmcnt(8)
	s_barrier
	s_waitcnt lgkmcnt(0)


	v_mfma_f32_16x16x32_bf16 v[124:127], v[128:131], v[144:147], v[124:127]
	v_mfma_f32_16x16x32_bf16 v[120:123], v[136:139], v[144:147], v[120:123]
	v_mfma_f32_16x16x32_bf16 v[116:119], v[128:131], v[152:155], v[116:119]
	v_mfma_f32_16x16x32_bf16 v[104:107], v[136:139], v[152:155], v[104:107]
	v_mfma_f32_16x16x32_bf16 v[96:99], v[128:131], v[180:183], v[96:99]
	v_mfma_f32_16x16x32_bf16 v[88:91], v[136:139], v[180:183], v[88:91]
	v_mfma_f32_16x16x32_bf16 v[80:83], v[128:131], v[194:197], v[80:83]
	v_mfma_f32_16x16x32_bf16 v[72:75], v[136:139], v[194:197], v[72:75]
	v_mfma_f32_16x16x32_bf16 v[124:127], v[132:135], v[148:151], v[124:127]
	v_mfma_f32_16x16x32_bf16 v[120:123], v[140:143], v[148:151], v[120:123]
	v_mfma_f32_16x16x32_bf16 v[116:119], v[132:135], v[156:159], v[116:119]
	v_mfma_f32_16x16x32_bf16 v[104:107], v[140:143], v[156:159], v[104:107]
	v_mfma_f32_16x16x32_bf16 v[96:99], v[132:135], v[184:187], v[96:99]
	v_mfma_f32_16x16x32_bf16 v[88:91], v[140:143], v[184:187], v[88:91]
	v_mfma_f32_16x16x32_bf16 v[80:83], v[132:135], v[198:201], v[80:83]
	v_mfma_f32_16x16x32_bf16 v[72:75], v[140:143], v[198:201], v[72:75]

	s_barrier
	s_add_i32 s38, 0, 0x1c000
	s_add_i32 s39, s63, s42
	v_add_u32_e32 v160, s38, v177
	v_lshl_add_u64 v[166:167], v[166:167], 0, s[14:15]
	s_mov_b32 m0, s39
	ds_read_b128 v[202:205], v160
	ds_read_b128 v[206:209], v160 offset:1024
	ds_read_b128 v[222:225], v160 offset:2048
	ds_read_b128 v[226:229], v160 offset:3072
	global_load_lds_dwordx4 v[166:167], off
	v_lshl_add_u64 v[166:167], v[188:189], 0, s[14:15]
	s_add_i32 m0, s39, 0x2000
	s_nop 0
	global_load_lds_dwordx4 v[166:167], off
	s_barrier
	s_waitcnt lgkmcnt(0)


	v_mfma_f32_16x16x32_bf16 v[112:115], v[202:205], v[144:147], v[112:115]
	v_mfma_f32_16x16x32_bf16 v[108:111], v[222:225], v[144:147], v[108:111]
	v_mfma_f32_16x16x32_bf16 v[100:103], v[202:205], v[152:155], v[100:103]
	v_mfma_f32_16x16x32_bf16 v[92:95], v[222:225], v[152:155], v[92:95]
	v_mfma_f32_16x16x32_bf16 v[84:87], v[202:205], v[180:183], v[84:87]
	v_mfma_f32_16x16x32_bf16 v[76:79], v[222:225], v[180:183], v[76:79]
	v_mfma_f32_16x16x32_bf16 v[68:71], v[202:205], v[194:197], v[68:71]
	v_mfma_f32_16x16x32_bf16 v[64:67], v[222:225], v[194:197], v[64:67]
	v_mfma_f32_16x16x32_bf16 v[112:115], v[206:209], v[148:151], v[112:115]
	v_mfma_f32_16x16x32_bf16 v[108:111], v[226:229], v[148:151], v[108:111]
	v_mfma_f32_16x16x32_bf16 v[100:103], v[206:209], v[156:159], v[100:103]
	v_mfma_f32_16x16x32_bf16 v[92:95], v[226:229], v[156:159], v[92:95]
	v_mfma_f32_16x16x32_bf16 v[84:87], v[206:209], v[184:187], v[84:87]
	v_mfma_f32_16x16x32_bf16 v[76:79], v[226:229], v[184:187], v[76:79]
	v_mfma_f32_16x16x32_bf16 v[68:71], v[206:209], v[198:201], v[68:71]
	v_mfma_f32_16x16x32_bf16 v[64:67], v[226:229], v[198:201], v[64:67]

	s_mov_b32 m0, s48
	v_lshl_add_u64 v[166:167], v[230:231], 0, s[14:15]
	s_barrier
	ds_read_b128 v[144:147], v190 offset:49152
	ds_read_b128 v[148:151], v190 offset:50176
	ds_read_b128 v[152:155], v190 offset:51200
	ds_read_b128 v[156:159], v190 offset:52224
	ds_read_b128 v[180:183], v190 offset:53248
	ds_read_b128 v[184:187], v190 offset:54272
	ds_read_b128 v[194:197], v190 offset:55296
	ds_read_b128 v[198:201], v190 offset:56320
	global_load_lds_dwordx4 v[166:167], off
	v_lshl_add_u64 v[166:167], v[232:233], 0, s[14:15]
	s_mov_b32 m0, s49
	s_nop 0
	global_load_lds_dwordx4 v[166:167], off
	s_barrier
	s_waitcnt lgkmcnt(0)


	v_mfma_f32_16x16x32_bf16 v[60:63], v[128:131], v[144:147], v[60:63]
	v_mfma_f32_16x16x32_bf16 v[56:59], v[136:139], v[144:147], v[56:59]
	v_mfma_f32_16x16x32_bf16 v[52:55], v[128:131], v[152:155], v[52:55]
	v_mfma_f32_16x16x32_bf16 v[40:43], v[136:139], v[152:155], v[40:43]
	v_mfma_f32_16x16x32_bf16 v[36:39], v[128:131], v[180:183], v[36:39]
	v_mfma_f32_16x16x32_bf16 v[24:27], v[136:139], v[180:183], v[24:27]
	v_mfma_f32_16x16x32_bf16 v[20:23], v[128:131], v[194:197], v[20:23]
	v_mfma_f32_16x16x32_bf16 v[8:11], v[136:139], v[194:197], v[8:11]
	v_mfma_f32_16x16x32_bf16 v[60:63], v[132:135], v[148:151], v[60:63]
	v_mfma_f32_16x16x32_bf16 v[56:59], v[140:143], v[148:151], v[56:59]
	v_mfma_f32_16x16x32_bf16 v[52:55], v[132:135], v[156:159], v[52:55]
	v_mfma_f32_16x16x32_bf16 v[40:43], v[140:143], v[156:159], v[40:43]
	v_mfma_f32_16x16x32_bf16 v[36:39], v[132:135], v[184:187], v[36:39]
	v_mfma_f32_16x16x32_bf16 v[24:27], v[140:143], v[184:187], v[24:27]
	v_mfma_f32_16x16x32_bf16 v[20:23], v[132:135], v[198:201], v[20:23]
	v_mfma_f32_16x16x32_bf16 v[8:11], v[140:143], v[198:201], v[8:11]

	s_barrier
	s_add_u32 s36, s36, 0x80080
	s_addc_u32 s37, s37, 0
	s_add_i32 s38, s38, s42
	v_lshl_add_u64 v[128:129], s[36:37], 0, v[172:173]
	s_mov_b32 m0, s38
	s_nop 0
	global_load_lds_dwordx4 v[128:129], off
	v_lshl_add_u64 v[128:129], s[36:37], 0, v[174:175]
	s_add_i32 m0, s38, 0x2000
	s_nop 0
	global_load_lds_dwordx4 v[128:129], off
	s_waitcnt vmcnt(6)
	s_barrier

	v_mfma_f32_16x16x32_bf16 v[48:51], v[202:205], v[144:147], v[48:51]
	v_mfma_f32_16x16x32_bf16 v[44:47], v[222:225], v[144:147], v[44:47]
	v_mfma_f32_16x16x32_bf16 v[32:35], v[202:205], v[152:155], v[32:35]
	v_mfma_f32_16x16x32_bf16 v[28:31], v[222:225], v[152:155], v[28:31]
	v_mfma_f32_16x16x32_bf16 v[16:19], v[202:205], v[180:183], v[16:19]
	v_mfma_f32_16x16x32_bf16 v[12:15], v[222:225], v[180:183], v[12:15]
	v_mfma_f32_16x16x32_bf16 v[4:7], v[202:205], v[194:197], v[4:7]
	v_mfma_f32_16x16x32_bf16 v[0:3], v[222:225], v[194:197], v[0:3]
	v_mfma_f32_16x16x32_bf16 v[48:51], v[206:209], v[148:151], v[48:51]
	v_mfma_f32_16x16x32_bf16 v[44:47], v[226:229], v[148:151], v[44:47]
	v_mfma_f32_16x16x32_bf16 v[32:35], v[206:209], v[156:159], v[32:35]
	v_mfma_f32_16x16x32_bf16 v[28:31], v[226:229], v[156:159], v[28:31]
	v_mfma_f32_16x16x32_bf16 v[16:19], v[206:209], v[184:187], v[16:19]
	v_mfma_f32_16x16x32_bf16 v[12:15], v[226:229], v[184:187], v[12:15]
	v_mfma_f32_16x16x32_bf16 v[4:7], v[206:209], v[198:201], v[4:7]
	v_mfma_f32_16x16x32_bf16 v[0:3], v[226:229], v[198:201], v[0:3]

	s_add_u32 s4, s4, 0x100
	s_addc_u32 s5, s5, 0
	s_add_u32 s60, s60, 0x100
	s_addc_u32 s61, s61, 0
	s_cmp_ge_i32 s62, s17
	s_mov_b32 s36, s62
	s_barrier
	s_cbranch_scc0 .LBB0_1024
	v_mov_b32_e32 v128, v210
	v_mov_b32_e32 v129, v169
	s_cmp_lt_i32 s12, 0
	v_lshl_add_u32 v128, v128, 4, v129
	v_ashrrev_i32_e32 v166, 2, v128
	v_and_b32_e32 v160, 3, v129
	v_and_b32_e32 v128, -4, v128
	v_lshl_add_u32 v193, v160, 6, v128
	s_mov_b64 s[4:5], -1
	s_cbranch_scc0 .LBB0_1043
	s_lshl_b32 s4, s30, 8
	v_lshl_or_b32 v128, v160, 2, s4
	s_lshl_b32 s4, s34, 8
	v_or_b32_e32 v180, s47, v128
	s_add_i32 s4, s4, s46
	v_readlane_b32 s60, v254, 6
	v_ashrrev_i32_e32 v181, 31, v180
	v_add_u32_e32 v184, s4, v166
	s_cmp_lt_i32 s34, 32
	v_readlane_b32 s61, v254, 7
	v_lshlrev_b64 v[128:129], 2, v[180:181]
	v_readlane_b32 s62, v254, 8
	v_readlane_b32 s63, v254, 9
	v_readlane_b32 s64, v254, 10
	v_readlane_b32 s65, v254, 11
	v_readlane_b32 s66, v254, 12
	v_readlane_b32 s67, v254, 13
	v_readlane_b32 s68, v254, 14
	v_readlane_b32 s69, v254, 15
	v_readlane_b32 s70, v254, 16
	v_readlane_b32 s71, v254, 17
	v_readlane_b32 s72, v254, 18
	v_readlane_b32 s73, v254, 19
	v_readlane_b32 s74, v254, 20
	v_readlane_b32 s75, v254, 21
	s_cselect_b32 s5, s61, s51
	s_cselect_b32 s4, s60, s50
	v_ashrrev_i32_e32 v185, 31, v184
	v_lshl_add_u64 v[182:183], s[4:5], 0, v[128:129]
	v_lshlrev_b64 v[130:131], 13, v[184:185]
	v_readlane_b32 s60, v254, 22
	v_lshl_add_u64 v[136:137], v[182:183], 0, v[130:131]
	v_readlane_b32 s61, v254, 23
	v_readlane_b32 s68, v254, 30
	v_readlane_b32 s69, v254, 31
	global_load_dwordx4 v[196:199], v[136:137], off nt
	global_load_dwordx4 v[200:203], v[136:137], off offset:64 nt
	global_load_dwordx4 v[204:207], v[136:137], off offset:512 nt
	s_mov_b64 s[60:61], s[68:69]
	v_lshl_add_u64 v[138:139], s[60:61], 0, v[128:129]
	global_load_dwordx4 v[140:143], v[138:139], off
	global_load_dwordx4 v[132:135], v[138:139], off offset:64
	global_load_dwordx4 v[128:131], v[138:139], off offset:512
	global_load_dwordx4 v[222:225], v[136:137], off offset:576 nt
	v_and_b32_e32 v145, 64, v192
	global_load_dwordx4 v[136:139], v[138:139], off offset:576
	v_xor_b32_e32 v144, 1, v192
	v_add_u32_e32 v194, 64, v145
	v_add_u32_e32 v186, 16, v184
	v_cmp_lt_i32_e64 s[4:5], v144, v194
	v_ashrrev_i32_e32 v187, 31, v186
	ds_bpermute_b32 v188, v193, v124
	v_cndmask_b32_e64 v195, v192, v144, s[4:5]
	v_lshlrev_b64 v[144:145], 13, v[186:187]
	v_lshl_add_u64 v[144:145], v[182:183], 0, v[144:145]
	global_load_dwordx4 v[156:159], v[144:145], off nt
	global_load_dwordx4 v[152:155], v[144:145], off offset:64 nt
	global_load_dwordx4 v[148:151], v[144:145], off offset:512 nt
	s_nop 0
	global_load_dwordx4 v[144:147], v[144:145], off offset:576 nt
	ds_bpermute_b32 v189, v193, v125
	ds_bpermute_b32 v208, v193, v126
	ds_bpermute_b32 v209, v193, v127
	ds_bpermute_b32 v226, v193, v120
	ds_bpermute_b32 v227, v193, v121
	ds_bpermute_b32 v228, v193, v122
	ds_bpermute_b32 v229, v193, v123
	ds_bpermute_b32 v230, v193, v112
	ds_bpermute_b32 v231, v193, v113
	v_readlane_b32 s64, v254, 26
	v_readlane_b32 s65, v254, 27
	v_readlane_b32 s66, v254, 28
	v_readlane_b32 s67, v254, 29
	v_readlane_b32 s72, v254, 34
	v_readlane_b32 s73, v254, 35
	v_readlane_b32 s74, v254, 36
	v_readlane_b32 s75, v254, 37
	s_mov_b64 s[64:65], s[72:73]
	ds_bpermute_b32 v232, v193, v114
	ds_bpermute_b32 v233, v193, v115
	v_lshlrev_b64 v[234:235], 11, v[184:185]
	s_mov_b64 s[66:67], s[74:75]
	v_lshl_add_u64 v[234:235], v[234:235], 0, v[180:181]
	v_xor_b32_e32 v167, 2, v192
	v_lshl_add_u64 v[236:237], v[234:235], 2, s[66:67]
	v_readlane_b32 s2, v254, 54
	v_cmp_lt_i32_e64 s[4:5], v167, v194
	v_lshlrev_b32_e32 v194, 2, v195
	v_lshlrev_b64 v[234:235], 1, v[234:235]
	v_readlane_b32 s3, v254, 55
	v_or_b32_e32 v240, 32, v234
	v_mov_b32_e32 v241, v235
	v_lshl_add_u64 v[238:239], s[2:3], 0, v[234:235]
	v_lshl_add_u64 v[240:241], s[2:3], 0, v[240:241]
	v_cndmask_b32_e64 v167, v192, v167, s[4:5]
	v_lshlrev_b32_e32 v167, 2, v167
	v_cmp_eq_u32_e32 vcc, 0, v160
	v_readlane_b32 s62, v254, 24
	v_readlane_b32 s63, v254, 25
	v_readlane_b32 s70, v254, 32
	v_readlane_b32 s71, v254, 33
	s_waitcnt vmcnt(0) lgkmcnt(0)
	v_pk_add_f32 v[198:199], v[198:199], v[208:209]
	v_pk_add_f32 v[196:197], v[196:197], v[188:189]
	v_pk_add_f32 v[202:203], v[202:203], v[228:229]
	v_pk_add_f32 v[200:201], v[200:201], v[226:227]
	v_pk_add_f32 v[204:205], v[204:205], v[230:231]
	v_mul_f32_e32 v195, v197, v197
	v_mul_f32_e32 v221, v199, v199
	global_store_dwordx4 v[236:237], v[196:199], off
	v_pk_mul_f32 v[188:189], v[142:143], v[198:199]
	v_pk_mul_f32 v[208:209], v[140:141], v[196:197]
	v_mul_f32_e32 v199, v201, v201
	v_mul_f32_e32 v230, v203, v203
	v_pk_mul_f32 v[226:227], v[134:135], v[202:203]
	v_pk_mul_f32 v[228:229], v[132:133], v[200:201]
	v_fmac_f32_e32 v195, v196, v196
	v_fmac_f32_e32 v221, v198, v198
	v_cvt_pk_bf16_f32 v196, v208, v209
	v_cvt_pk_bf16_f32 v197, v188, v189
	v_fmac_f32_e32 v199, v200, v200
	v_fmac_f32_e32 v230, v202, v202
	v_pk_add_f32 v[206:207], v[206:207], v[232:233]
	v_cvt_pk_bf16_f32 v188, v228, v229
	v_cvt_pk_bf16_f32 v189, v226, v227
	v_add_f32_e32 v195, v195, v221
	global_store_dwordx2 v[238:239], v[196:197], off
	v_add_f32_e32 v196, v199, v230
	global_store_dwordx4 v[236:237], v[200:203], off offset:64
	global_store_dwordx2 v[240:241], v[188:189], off
	v_add_f32_e32 v188, v195, v196
	v_mul_f32_e32 v189, v205, v205
	v_mul_f32_e32 v195, v207, v207
	v_fmac_f32_e32 v189, v204, v204
	v_fmac_f32_e32 v195, v206, v206
	ds_bpermute_b32 v200, v193, v108
	ds_bpermute_b32 v198, v193, v110
	ds_bpermute_b32 v199, v193, v111
	ds_bpermute_b32 v201, v193, v109
	v_add_f32_e32 v189, v189, v195
	v_add_f32_e32 v195, v188, v189
	v_pk_mul_f32 v[188:189], v[130:131], v[206:207]
	v_pk_mul_f32 v[196:197], v[128:129], v[204:205]
	global_store_dwordx4 v[236:237], v[204:207], off offset:512
	v_cvt_pk_bf16_f32 v196, v196, v197
	v_cvt_pk_bf16_f32 v197, v188, v189
	v_or_b32_e32 v188, 0x100, v234
	v_mov_b32_e32 v189, v235
	v_lshl_add_u64 v[188:189], s[2:3], 0, v[188:189]
	global_store_dwordx2 v[188:189], v[196:197], off
	s_waitcnt lgkmcnt(1)
	v_pk_add_f32 v[198:199], v[224:225], v[198:199]
	s_waitcnt lgkmcnt(0)
	v_pk_add_f32 v[196:197], v[222:223], v[200:201]
	v_mul_f32_e32 v189, v199, v199
	v_mul_f32_e32 v188, v197, v197
	v_fmac_f32_e32 v188, v196, v196
	v_fmac_f32_e32 v189, v198, v198
	v_add_f32_e32 v188, v188, v189
	v_add_f32_e32 v195, v195, v188
	ds_bpermute_b32 v200, v194, v195
	v_pk_mul_f32 v[188:189], v[136:137], v[196:197]
	global_store_dwordx4 v[236:237], v[196:199], off offset:576
	v_or_b32_e32 v234, 0x120, v234
	s_nop 0
	v_cvt_pk_bf16_f32 v196, v188, v189
	s_waitcnt lgkmcnt(0)
	v_add_f32_e32 v188, v195, v200
	ds_bpermute_b32 v189, v167, v188
	v_pk_mul_f32 v[198:199], v[138:139], v[198:199]
	s_nop 0
	v_cvt_pk_bf16_f32 v197, v198, v199
	v_lshl_add_u64 v[198:199], s[2:3], 0, v[234:235]
	global_store_dwordx2 v[198:199], v[196:197], off
	s_and_saveexec_b64 s[4:5], vcc
	s_cbranch_execz .LBB0_1028
	s_waitcnt lgkmcnt(0)
	v_add_f32_e32 v195, v188, v189
	s_lshl_b32 s36, s30, 2
	v_lshlrev_b64 v[188:189], 7, v[184:185]
	s_ashr_i32 s37, s36, 31
	v_lshl_add_u64 v[188:189], s[10:11], 0, v[188:189]
	v_lshl_add_u64 v[188:189], s[36:37], 2, v[188:189]
	s_lshl_b32 s36, s45, 2
	s_mov_b32 s37, s13
	v_lshl_add_u64 v[188:189], v[188:189], 0, s[36:37]
	global_store_dword v[188:189], v195, off

.LBB0_1167:
	ds_read_b128 v[148:151], v143
	ds_read_b128 v[152:155], v143 offset:1024
	ds_read_b128 v[156:159], v143 offset:2048
	ds_read_b128 v[160:163], v143 offset:3072
	s_add_u32 s24, s22, 0xfff80080
	s_addc_u32 s25, s23, -1
	s_cmp_eq_u32 s53, 28
	s_cselect_b32 s27, s15, s25
	s_cselect_b32 s26, s49, s24
	s_cselect_b32 s25, s13, s52
	s_cselect_b32 s24, s50, s51
	v_lshl_add_u64 v[136:137], s[22:23], 0, v[128:129]
	s_add_i32 m0, s21, 0xc000
	ds_read_b128 v[164:167], v145
	ds_read_b128 v[176:179], v145 offset:1024
	ds_read_b128 v[180:183], v145 offset:2048
	ds_read_b128 v[184:187], v145 offset:3072
	ds_read_b128 v[188:191], v145 offset:4096
	ds_read_b128 v[192:195], v145 offset:5120
	ds_read_b128 v[196:199], v145 offset:6144
	ds_read_b128 v[200:203], v145 offset:7168
	global_load_lds_dwordx4 v[136:137], off
	v_lshl_add_u64 v[136:137], s[22:23], 0, v[130:131]
	s_add_i32 m0, s21, 0xe000
	s_nop 0
	global_load_lds_dwordx4 v[136:137], off
	s_waitcnt lgkmcnt(8)
	s_barrier
	s_waitcnt lgkmcnt(0)


	v_mfma_f32_16x16x32_bf16 v[124:127], v[148:151], v[164:167], v[124:127]
	v_mfma_f32_16x16x32_bf16 v[120:123], v[156:159], v[164:167], v[120:123]
	v_mfma_f32_16x16x32_bf16 v[116:119], v[148:151], v[180:183], v[116:119]
	v_mfma_f32_16x16x32_bf16 v[104:107], v[156:159], v[180:183], v[104:107]
	v_mfma_f32_16x16x32_bf16 v[96:99], v[148:151], v[188:191], v[96:99]
	v_mfma_f32_16x16x32_bf16 v[88:91], v[156:159], v[188:191], v[88:91]
	v_mfma_f32_16x16x32_bf16 v[80:83], v[148:151], v[196:199], v[80:83]
	v_mfma_f32_16x16x32_bf16 v[72:75], v[156:159], v[196:199], v[72:75]
	v_mfma_f32_16x16x32_bf16 v[124:127], v[152:155], v[176:179], v[124:127]
	v_mfma_f32_16x16x32_bf16 v[120:123], v[160:163], v[176:179], v[120:123]
	v_mfma_f32_16x16x32_bf16 v[116:119], v[152:155], v[184:187], v[116:119]
	v_mfma_f32_16x16x32_bf16 v[104:107], v[160:163], v[184:187], v[104:107]
	v_mfma_f32_16x16x32_bf16 v[96:99], v[152:155], v[192:195], v[96:99]
	v_mfma_f32_16x16x32_bf16 v[88:91], v[160:163], v[192:195], v[88:91]
	v_mfma_f32_16x16x32_bf16 v[80:83], v[152:155], v[200:203], v[80:83]
	v_mfma_f32_16x16x32_bf16 v[72:75], v[160:163], v[200:203], v[72:75]

	s_barrier
	s_add_i32 s54, s45, s31
	v_lshl_add_u64 v[136:137], s[24:25], 0, v[172:173]
	s_mov_b32 m0, s54
	ds_read_b128 v[204:207], v147
	ds_read_b128 v[218:221], v147 offset:1024
	ds_read_b128 v[222:225], v147 offset:2048
	ds_read_b128 v[226:229], v147 offset:3072
	global_load_lds_dwordx4 v[136:137], off
	v_lshl_add_u64 v[140:141], s[24:25], 0, v[174:175]
	s_add_i32 m0, s54, 0x2000
	s_nop 0
	global_load_lds_dwordx4 v[140:141], off
	s_barrier
	s_waitcnt lgkmcnt(0)


	v_mfma_f32_16x16x32_bf16 v[112:115], v[204:207], v[164:167], v[112:115]
	v_mfma_f32_16x16x32_bf16 v[108:111], v[222:225], v[164:167], v[108:111]
	v_mfma_f32_16x16x32_bf16 v[100:103], v[204:207], v[180:183], v[100:103]
	v_mfma_f32_16x16x32_bf16 v[92:95], v[222:225], v[180:183], v[92:95]
	v_mfma_f32_16x16x32_bf16 v[84:87], v[204:207], v[188:191], v[84:87]
	v_mfma_f32_16x16x32_bf16 v[76:79], v[222:225], v[188:191], v[76:79]
	v_mfma_f32_16x16x32_bf16 v[68:71], v[204:207], v[196:199], v[68:71]
	v_mfma_f32_16x16x32_bf16 v[64:67], v[222:225], v[196:199], v[64:67]
	v_mfma_f32_16x16x32_bf16 v[112:115], v[218:221], v[176:179], v[112:115]
	v_mfma_f32_16x16x32_bf16 v[108:111], v[226:229], v[176:179], v[108:111]
	v_mfma_f32_16x16x32_bf16 v[100:103], v[218:221], v[184:187], v[100:103]
	v_mfma_f32_16x16x32_bf16 v[92:95], v[226:229], v[184:187], v[92:95]
	v_mfma_f32_16x16x32_bf16 v[84:87], v[218:221], v[192:195], v[84:87]
	v_mfma_f32_16x16x32_bf16 v[76:79], v[226:229], v[192:195], v[76:79]
	v_mfma_f32_16x16x32_bf16 v[68:71], v[218:221], v[200:203], v[68:71]
	v_mfma_f32_16x16x32_bf16 v[64:67], v[226:229], v[200:203], v[64:67]

	s_mov_b32 m0, s21
	v_lshl_add_u64 v[208:209], s[26:27], 0, v[172:173]
	s_barrier
	ds_read_b128 v[164:167], v145 offset:16384
	ds_read_b128 v[176:179], v145 offset:17408
	ds_read_b128 v[180:183], v145 offset:18432
	ds_read_b128 v[184:187], v145 offset:19456
	ds_read_b128 v[188:191], v145 offset:20480
	ds_read_b128 v[192:195], v145 offset:21504
	ds_read_b128 v[196:199], v145 offset:22528
	ds_read_b128 v[200:203], v145 offset:23552
	global_load_lds_dwordx4 v[208:209], off
	v_lshl_add_u64 v[230:231], s[26:27], 0, v[174:175]
	s_mov_b32 m0, s35
	s_nop 0
	global_load_lds_dwordx4 v[230:231], off
	s_barrier
	s_waitcnt lgkmcnt(0)


	v_mfma_f32_16x16x32_bf16 v[60:63], v[148:151], v[164:167], v[60:63]
	v_mfma_f32_16x16x32_bf16 v[56:59], v[156:159], v[164:167], v[56:59]
	v_mfma_f32_16x16x32_bf16 v[48:51], v[148:151], v[180:183], v[48:51]
	v_mfma_f32_16x16x32_bf16 v[40:43], v[156:159], v[180:183], v[40:43]
	v_mfma_f32_16x16x32_bf16 v[32:35], v[148:151], v[188:191], v[32:35]
	v_mfma_f32_16x16x32_bf16 v[24:27], v[156:159], v[188:191], v[24:27]
	v_mfma_f32_16x16x32_bf16 v[16:19], v[148:151], v[196:199], v[16:19]
	v_mfma_f32_16x16x32_bf16 v[8:11], v[156:159], v[196:199], v[8:11]
	v_mfma_f32_16x16x32_bf16 v[60:63], v[152:155], v[176:179], v[60:63]
	v_mfma_f32_16x16x32_bf16 v[56:59], v[160:163], v[176:179], v[56:59]
	v_mfma_f32_16x16x32_bf16 v[48:51], v[152:155], v[184:187], v[48:51]
	v_mfma_f32_16x16x32_bf16 v[40:43], v[160:163], v[184:187], v[40:43]
	v_mfma_f32_16x16x32_bf16 v[32:35], v[152:155], v[192:195], v[32:35]
	v_mfma_f32_16x16x32_bf16 v[24:27], v[160:163], v[192:195], v[24:27]
	v_mfma_f32_16x16x32_bf16 v[16:19], v[152:155], v[200:203], v[16:19]
	v_mfma_f32_16x16x32_bf16 v[8:11], v[160:163], v[200:203], v[8:11]

	s_barrier
	s_add_u32 s54, s24, 0x80000
	s_addc_u32 s55, s25, 0
	s_add_i32 s56, s46, s31
	v_lshl_add_u64 v[148:149], s[54:55], 0, v[172:173]
	s_mov_b32 m0, s56
	s_nop 0
	global_load_lds_dwordx4 v[148:149], off
	v_lshl_add_u64 v[148:149], s[54:55], 0, v[174:175]
	s_add_i32 m0, s56, 0x2000
	s_nop 0
	global_load_lds_dwordx4 v[148:149], off
	s_waitcnt vmcnt(6)
	s_barrier

	v_mfma_f32_16x16x32_bf16 v[52:55], v[204:207], v[164:167], v[52:55]
	v_mfma_f32_16x16x32_bf16 v[44:47], v[222:225], v[164:167], v[44:47]
	v_mfma_f32_16x16x32_bf16 v[36:39], v[204:207], v[180:183], v[36:39]
	v_mfma_f32_16x16x32_bf16 v[28:31], v[222:225], v[180:183], v[28:31]
	v_mfma_f32_16x16x32_bf16 v[20:23], v[204:207], v[188:191], v[20:23]
	v_mfma_f32_16x16x32_bf16 v[12:15], v[222:225], v[188:191], v[12:15]
	v_mfma_f32_16x16x32_bf16 v[4:7], v[204:207], v[196:199], v[4:7]
	v_mfma_f32_16x16x32_bf16 v[0:3], v[222:225], v[196:199], v[0:3]
	v_mfma_f32_16x16x32_bf16 v[52:55], v[218:221], v[176:179], v[52:55]
	v_mfma_f32_16x16x32_bf16 v[44:47], v[226:229], v[176:179], v[44:47]
	v_mfma_f32_16x16x32_bf16 v[36:39], v[218:221], v[184:187], v[36:39]
	v_mfma_f32_16x16x32_bf16 v[28:31], v[226:229], v[184:187], v[28:31]
	v_mfma_f32_16x16x32_bf16 v[20:23], v[218:221], v[192:195], v[20:23]
	v_mfma_f32_16x16x32_bf16 v[12:15], v[226:229], v[192:195], v[12:15]
	v_mfma_f32_16x16x32_bf16 v[4:7], v[218:221], v[200:203], v[4:7]
	v_mfma_f32_16x16x32_bf16 v[0:3], v[226:229], v[200:203], v[0:3]

	s_add_i32 s54, 0, 0x18000
	v_add_u32_e32 v138, s54, v139
	s_barrier
	ds_read_b128 v[148:151], v138
	ds_read_b128 v[152:155], v138 offset:1024
	ds_read_b128 v[156:159], v138 offset:2048
	ds_read_b128 v[160:163], v138 offset:3072
	s_add_u32 s26, s26, 0x80000
	s_addc_u32 s27, s27, 0
	s_mov_b32 m0, s36
	v_lshl_add_u64 v[204:205], s[26:27], 0, v[172:173]
	ds_read_b128 v[164:167], v145 offset:32768
	ds_read_b128 v[176:179], v145 offset:33792
	ds_read_b128 v[180:183], v145 offset:34816
	ds_read_b128 v[184:187], v145 offset:35840
	ds_read_b128 v[188:191], v145 offset:36864
	ds_read_b128 v[192:195], v145 offset:37888
	ds_read_b128 v[196:199], v145 offset:38912
	ds_read_b128 v[200:203], v145 offset:39936
	global_load_lds_dwordx4 v[204:205], off
	v_lshl_add_u64 v[204:205], s[26:27], 0, v[174:175]
	s_mov_b32 m0, s37
	s_nop 0
	global_load_lds_dwordx4 v[204:205], off
	s_waitcnt lgkmcnt(8)
	s_barrier
	s_waitcnt lgkmcnt(0)


	v_mfma_f32_16x16x32_bf16 v[124:127], v[148:151], v[164:167], v[124:127]
	v_mfma_f32_16x16x32_bf16 v[120:123], v[156:159], v[164:167], v[120:123]
	v_mfma_f32_16x16x32_bf16 v[116:119], v[148:151], v[180:183], v[116:119]
	v_mfma_f32_16x16x32_bf16 v[104:107], v[156:159], v[180:183], v[104:107]
	v_mfma_f32_16x16x32_bf16 v[96:99], v[148:151], v[188:191], v[96:99]
	v_mfma_f32_16x16x32_bf16 v[88:91], v[156:159], v[188:191], v[88:91]
	v_mfma_f32_16x16x32_bf16 v[80:83], v[148:151], v[196:199], v[80:83]
	v_mfma_f32_16x16x32_bf16 v[72:75], v[156:159], v[196:199], v[72:75]
	v_mfma_f32_16x16x32_bf16 v[124:127], v[152:155], v[176:179], v[124:127]
	v_mfma_f32_16x16x32_bf16 v[120:123], v[160:163], v[176:179], v[120:123]
	v_mfma_f32_16x16x32_bf16 v[116:119], v[152:155], v[184:187], v[116:119]
	v_mfma_f32_16x16x32_bf16 v[104:107], v[160:163], v[184:187], v[104:107]
	v_mfma_f32_16x16x32_bf16 v[96:99], v[152:155], v[192:195], v[96:99]
	v_mfma_f32_16x16x32_bf16 v[88:91], v[160:163], v[192:195], v[88:91]
	v_mfma_f32_16x16x32_bf16 v[80:83], v[152:155], v[200:203], v[80:83]
	v_mfma_f32_16x16x32_bf16 v[72:75], v[160:163], v[200:203], v[72:75]

	s_barrier
	s_add_i32 s26, 0, 0x1c000
	s_add_i32 s27, s54, s31
	v_add_u32_e32 v138, s26, v139
	v_lshl_add_u64 v[136:137], v[136:137], 0, s[10:11]
	s_mov_b32 m0, s27
	ds_read_b128 v[204:207], v138
	ds_read_b128 v[218:221], v138 offset:1024
	ds_read_b128 v[222:225], v138 offset:2048
	ds_read_b128 v[226:229], v138 offset:3072
	global_load_lds_dwordx4 v[136:137], off
	v_lshl_add_u64 v[136:137], v[140:141], 0, s[10:11]
	s_add_i32 m0, s27, 0x2000
	s_nop 0
	global_load_lds_dwordx4 v[136:137], off
	s_barrier
	s_waitcnt lgkmcnt(0)


	v_mfma_f32_16x16x32_bf16 v[112:115], v[204:207], v[164:167], v[112:115]
	v_mfma_f32_16x16x32_bf16 v[108:111], v[222:225], v[164:167], v[108:111]
	v_mfma_f32_16x16x32_bf16 v[100:103], v[204:207], v[180:183], v[100:103]
	v_mfma_f32_16x16x32_bf16 v[92:95], v[222:225], v[180:183], v[92:95]
	v_mfma_f32_16x16x32_bf16 v[84:87], v[204:207], v[188:191], v[84:87]
	v_mfma_f32_16x16x32_bf16 v[76:79], v[222:225], v[188:191], v[76:79]
	v_mfma_f32_16x16x32_bf16 v[68:71], v[204:207], v[196:199], v[68:71]
	v_mfma_f32_16x16x32_bf16 v[64:67], v[222:225], v[196:199], v[64:67]
	v_mfma_f32_16x16x32_bf16 v[112:115], v[218:221], v[176:179], v[112:115]
	v_mfma_f32_16x16x32_bf16 v[108:111], v[226:229], v[176:179], v[108:111]
	v_mfma_f32_16x16x32_bf16 v[100:103], v[218:221], v[184:187], v[100:103]
	v_mfma_f32_16x16x32_bf16 v[92:95], v[226:229], v[184:187], v[92:95]
	v_mfma_f32_16x16x32_bf16 v[84:87], v[218:221], v[192:195], v[84:87]
	v_mfma_f32_16x16x32_bf16 v[76:79], v[226:229], v[192:195], v[76:79]
	v_mfma_f32_16x16x32_bf16 v[68:71], v[218:221], v[200:203], v[68:71]
	v_mfma_f32_16x16x32_bf16 v[64:67], v[226:229], v[200:203], v[64:67]

	s_mov_b32 m0, s41
	v_lshl_add_u64 v[136:137], v[208:209], 0, s[10:11]
	s_barrier
	ds_read_b128 v[164:167], v145 offset:49152
	ds_read_b128 v[176:179], v145 offset:50176
	ds_read_b128 v[180:183], v145 offset:51200
	ds_read_b128 v[184:187], v145 offset:52224
	ds_read_b128 v[188:191], v145 offset:53248
	ds_read_b128 v[192:195], v145 offset:54272
	ds_read_b128 v[196:199], v145 offset:55296
	ds_read_b128 v[200:203], v145 offset:56320
	global_load_lds_dwordx4 v[136:137], off
	v_lshl_add_u64 v[136:137], v[230:231], 0, s[10:11]
	s_mov_b32 m0, s42
	s_nop 0
	global_load_lds_dwordx4 v[136:137], off
	s_barrier
	s_waitcnt lgkmcnt(0)


	v_mfma_f32_16x16x32_bf16 v[60:63], v[148:151], v[164:167], v[60:63]
	v_mfma_f32_16x16x32_bf16 v[56:59], v[156:159], v[164:167], v[56:59]
	v_mfma_f32_16x16x32_bf16 v[48:51], v[148:151], v[180:183], v[48:51]
	v_mfma_f32_16x16x32_bf16 v[40:43], v[156:159], v[180:183], v[40:43]
	v_mfma_f32_16x16x32_bf16 v[32:35], v[148:151], v[188:191], v[32:35]
	v_mfma_f32_16x16x32_bf16 v[24:27], v[156:159], v[188:191], v[24:27]
	v_mfma_f32_16x16x32_bf16 v[16:19], v[148:151], v[196:199], v[16:19]
	v_mfma_f32_16x16x32_bf16 v[8:11], v[156:159], v[196:199], v[8:11]
	v_mfma_f32_16x16x32_bf16 v[60:63], v[152:155], v[176:179], v[60:63]
	v_mfma_f32_16x16x32_bf16 v[56:59], v[160:163], v[176:179], v[56:59]
	v_mfma_f32_16x16x32_bf16 v[48:51], v[152:155], v[184:187], v[48:51]
	v_mfma_f32_16x16x32_bf16 v[40:43], v[160:163], v[184:187], v[40:43]
	v_mfma_f32_16x16x32_bf16 v[32:35], v[152:155], v[192:195], v[32:35]
	v_mfma_f32_16x16x32_bf16 v[24:27], v[160:163], v[192:195], v[24:27]
	v_mfma_f32_16x16x32_bf16 v[16:19], v[152:155], v[200:203], v[16:19]
	v_mfma_f32_16x16x32_bf16 v[8:11], v[160:163], v[200:203], v[8:11]

	s_barrier
	s_add_u32 s24, s24, 0x80080
	s_addc_u32 s25, s25, 0
	s_add_i32 s26, s26, s31
	v_lshl_add_u64 v[136:137], s[24:25], 0, v[172:173]
	s_mov_b32 m0, s26
	s_nop 0
	global_load_lds_dwordx4 v[136:137], off
	v_lshl_add_u64 v[136:137], s[24:25], 0, v[174:175]
	s_add_i32 m0, s26, 0x2000
	s_nop 0
	global_load_lds_dwordx4 v[136:137], off
	s_waitcnt vmcnt(6)
	s_barrier

	v_mfma_f32_16x16x32_bf16 v[52:55], v[204:207], v[164:167], v[52:55]
	v_mfma_f32_16x16x32_bf16 v[44:47], v[222:225], v[164:167], v[44:47]
	v_mfma_f32_16x16x32_bf16 v[36:39], v[204:207], v[180:183], v[36:39]
	v_mfma_f32_16x16x32_bf16 v[28:31], v[222:225], v[180:183], v[28:31]
	v_mfma_f32_16x16x32_bf16 v[20:23], v[204:207], v[188:191], v[20:23]
	v_mfma_f32_16x16x32_bf16 v[12:15], v[222:225], v[188:191], v[12:15]
	v_mfma_f32_16x16x32_bf16 v[4:7], v[204:207], v[196:199], v[4:7]
	v_mfma_f32_16x16x32_bf16 v[0:3], v[222:225], v[196:199], v[0:3]
	v_mfma_f32_16x16x32_bf16 v[52:55], v[218:221], v[176:179], v[52:55]
	v_mfma_f32_16x16x32_bf16 v[44:47], v[226:229], v[176:179], v[44:47]
	v_mfma_f32_16x16x32_bf16 v[36:39], v[218:221], v[184:187], v[36:39]
	v_mfma_f32_16x16x32_bf16 v[28:31], v[226:229], v[184:187], v[28:31]
	v_mfma_f32_16x16x32_bf16 v[20:23], v[218:221], v[192:195], v[20:23]
	v_mfma_f32_16x16x32_bf16 v[12:15], v[226:229], v[192:195], v[12:15]
	v_mfma_f32_16x16x32_bf16 v[4:7], v[218:221], v[200:203], v[4:7]
	v_mfma_f32_16x16x32_bf16 v[0:3], v[226:229], v[200:203], v[0:3]

	s_add_i32 s53, s53, 2
	s_add_u32 s22, s22, 0x100
	s_addc_u32 s23, s23, 0
	s_add_u32 s51, s51, 0x100
	s_addc_u32 s52, s52, 0
	s_cmp_gt_u32 s53, 29
	s_barrier
	s_cbranch_scc0 .LBB0_1167
	s_lshl_b32 s13, s20, 8
	v_mov_b32_e32 v138, v210
	v_mov_b32_e32 v142, v169
	s_add_i32 s13, s13, s39
	s_lshl_b32 s15, s48, 7
	v_add_u32_e32 v136, s13, v142
	v_ashrrev_i32_e32 v137, 31, v136
	v_lshl_add_u64 v[140:141], v[136:137], 2, s[2:3]
	global_load_dword v154, v[140:141], off
	global_load_dword v152, v[140:141], off offset:64
	v_lshl_add_u32 v138, v138, 4, v142
	v_and_b32_e32 v142, 3, v142
	v_ashrrev_i32_e32 v144, 2, v138
	v_and_b32_e32 v138, -4, v138
	v_lshl_or_b32 v146, v142, 2, s15
	v_add_u32_e32 v151, s13, v144
	v_lshl_add_u32 v149, v142, 6, v138
	v_or_b32_e32 v156, s40, v146
	global_load_dword v150, v[140:141], off offset:128
	global_load_dword v148, v[140:141], off offset:192
	global_load_dword v146, v[140:141], off offset:512
	global_load_dword v144, v[140:141], off offset:576
	global_load_dword v142, v[140:141], off offset:640
	global_load_dword v138, v[140:141], off offset:704
	v_mov_b64_e32 v[136:137], s[0:1]
	v_ashrrev_i32_e32 v157, 31, v156
	v_mad_i64_i32 v[158:159], s[22:23], v151, s47, v[136:137]
	v_lshlrev_b64 v[140:141], 1, v[156:157]
	v_lshl_add_u64 v[156:157], v[158:159], 0, v[140:141]
	v_add_u32_e32 v153, 16, v151
	s_and_b64 vcc, exec, s[4:5]
	s_mov_b32 s48, s12
	s_mov_b32 s20, s14
	s_mov_b64 s[24:25], s[18:19]
	s_waitcnt vmcnt(0)
	v_pk_mul_f32 v[126:127], v[126:127], v[154:155] op_sel_hi:[1,0]
	v_pk_mul_f32 v[124:125], v[124:125], v[154:155] op_sel_hi:[1,0]
	v_pk_mul_f32 v[114:115], v[114:115], v[154:155] op_sel_hi:[1,0]
	v_pk_mul_f32 v[112:113], v[112:113], v[154:155] op_sel_hi:[1,0]
	v_pk_mul_f32 v[122:123], v[122:123], v[154:155] op_sel_hi:[1,0]
	v_pk_mul_f32 v[120:121], v[120:121], v[154:155] op_sel_hi:[1,0]
	v_pk_mul_f32 v[110:111], v[110:111], v[154:155] op_sel_hi:[1,0]
	v_pk_mul_f32 v[108:109], v[108:109], v[154:155] op_sel_hi:[1,0]
	v_mul_f32_e32 v154, 0xbfb8aa3b, v124
	v_mul_f32_e32 v155, 0xbfb8aa3b, v125
	v_mul_f32_e32 v158, 0xbfb8aa3b, v126
	v_mul_f32_e32 v159, 0xbfb8aa3b, v127
	v_mul_f32_e32 v160, 0xbfb8aa3b, v120
	v_mul_f32_e32 v161, 0xbfb8aa3b, v121
	v_mul_f32_e32 v162, 0xbfb8aa3b, v122
	v_mul_f32_e32 v163, 0xbfb8aa3b, v123
	v_exp_f32_e32 v154, v154
	v_exp_f32_e32 v155, v155
	v_exp_f32_e32 v158, v158
	v_exp_f32_e32 v159, v159
	v_exp_f32_e32 v160, v160
	v_exp_f32_e32 v161, v161
	v_exp_f32_e32 v162, v162
	v_exp_f32_e32 v163, v163
	v_add_f32_e32 v154, 1.0, v154
	v_add_f32_e32 v155, 1.0, v155
	v_add_f32_e32 v158, 1.0, v158
	v_add_f32_e32 v159, 1.0, v159
	v_add_f32_e32 v160, 1.0, v160
	v_add_f32_e32 v161, 1.0, v161
	v_add_f32_e32 v162, 1.0, v162
	v_add_f32_e32 v163, 1.0, v163
	v_rcp_f32_e32 v154, v154
	v_rcp_f32_e32 v155, v155
	v_rcp_f32_e32 v158, v158
	v_rcp_f32_e32 v159, v159
	v_rcp_f32_e32 v160, v160
	v_rcp_f32_e32 v161, v161
	v_rcp_f32_e32 v162, v162
	v_rcp_f32_e32 v163, v163
	v_pk_mul_f32 v[124:125], v[124:125], v[154:155]
	v_pk_mul_f32 v[126:127], v[126:127], v[158:159]
	v_pk_mul_f32 v[120:121], v[120:121], v[160:161]
	v_pk_mul_f32 v[122:123], v[122:123], v[162:163]
	v_pk_mul_f32 v[112:113], v[112:113], v[124:125]
	v_pk_mul_f32 v[114:115], v[114:115], v[126:127]
	v_pk_mul_f32 v[118:119], v[118:119], v[152:153] op_sel_hi:[1,0]
	v_pk_mul_f32 v[116:117], v[116:117], v[152:153] op_sel_hi:[1,0]
	v_pk_mul_f32 v[108:109], v[108:109], v[120:121]
	v_pk_mul_f32 v[110:111], v[110:111], v[122:123]
	v_cvt_pk_bf16_f32 v112, v112, v113
	v_cvt_pk_bf16_f32 v113, v114, v115
	v_mul_f32_e32 v164, 0xbfb8aa3b, v116
	v_mul_f32_e32 v165, 0xbfb8aa3b, v117
	v_mul_f32_e32 v166, 0xbfb8aa3b, v118
	v_mul_f32_e32 v167, 0xbfb8aa3b, v119
	v_cvt_pk_bf16_f32 v114, v108, v109
	v_cvt_pk_bf16_f32 v111, v110, v111
	ds_bpermute_b32 v108, v149, v112
	ds_bpermute_b32 v109, v149, v113
	v_exp_f32_e32 v164, v164
	v_exp_f32_e32 v165, v165
	v_exp_f32_e32 v166, v166
	v_exp_f32_e32 v167, v167
	ds_bpermute_b32 v110, v149, v114
	ds_bpermute_b32 v111, v149, v111
	v_add_f32_e32 v164, 1.0, v164
	v_add_f32_e32 v113, 1.0, v165
	s_waitcnt lgkmcnt(0)
	global_store_dwordx2 v[156:157], v[108:109], off
	global_store_dwordx2 v[156:157], v[110:111], off offset:32
	v_add_f32_e32 v108, 1.0, v166
	v_add_f32_e32 v109, 1.0, v167
	v_rcp_f32_e32 v112, v164
	v_rcp_f32_e32 v113, v113
	v_rcp_f32_e32 v108, v108
	v_rcp_f32_e32 v109, v109
	v_pk_mul_f32 v[102:103], v[102:103], v[152:153] op_sel_hi:[1,0]
	v_pk_mul_f32 v[100:101], v[100:101], v[152:153] op_sel_hi:[1,0]
	v_pk_mul_f32 v[110:111], v[116:117], v[112:113]
	v_pk_mul_f32 v[108:109], v[118:119], v[108:109]
	v_pk_mul_f32 v[100:101], v[100:101], v[110:111]
	v_pk_mul_f32 v[102:103], v[102:103], v[108:109]
	v_cvt_pk_bf16_f32 v100, v100, v101
	v_cvt_pk_bf16_f32 v101, v102, v103
	v_pk_mul_f32 v[102:103], v[106:107], v[152:153] op_sel_hi:[1,0]
	v_pk_mul_f32 v[104:105], v[104:105], v[152:153] op_sel_hi:[1,0]
	v_mul_f32_e32 v108, 0xbfb8aa3b, v102
	v_mul_f32_e32 v106, 0xbfb8aa3b, v104
	v_mul_f32_e32 v107, 0xbfb8aa3b, v105
	v_mul_f32_e32 v109, 0xbfb8aa3b, v103
	v_exp_f32_e32 v106, v106
	v_exp_f32_e32 v107, v107
	v_exp_f32_e32 v108, v108
	v_exp_f32_e32 v109, v109
	v_add_f32_e32 v106, 1.0, v106
	v_add_f32_e32 v107, 1.0, v107
	v_add_f32_e32 v108, 1.0, v108
	v_add_f32_e32 v109, 1.0, v109
	v_rcp_f32_e32 v106, v106
	v_rcp_f32_e32 v107, v107
	v_rcp_f32_e32 v108, v108
	v_rcp_f32_e32 v109, v109
	v_pk_mul_f32 v[94:95], v[94:95], v[152:153] op_sel_hi:[1,0]
	v_pk_mul_f32 v[92:93], v[92:93], v[152:153] op_sel_hi:[1,0]
	v_pk_mul_f32 v[104:105], v[104:105], v[106:107]
	v_pk_mul_f32 v[102:103], v[102:103], v[108:109]
	v_pk_mul_f32 v[92:93], v[92:93], v[104:105]
	v_pk_mul_f32 v[94:95], v[94:95], v[102:103]
	ds_bpermute_b32 v100, v149, v100
	ds_bpermute_b32 v101, v149, v101
	v_cvt_pk_bf16_f32 v92, v92, v93
	v_cvt_pk_bf16_f32 v93, v94, v95
	ds_bpermute_b32 v92, v149, v92
	ds_bpermute_b32 v93, v149, v93
	v_mad_i64_i32 v[94:95], s[22:23], v153, s47, v[136:137]
	v_lshl_add_u64 v[94:95], v[94:95], 0, v[140:141]
	s_waitcnt lgkmcnt(2)
	global_store_dwordx2 v[94:95], v[100:101], off
	s_waitcnt lgkmcnt(0)
	global_store_dwordx2 v[94:95], v[92:93], off offset:32
	v_pk_mul_f32 v[92:93], v[98:99], v[150:151] op_sel_hi:[1,0]
	v_pk_mul_f32 v[94:95], v[96:97], v[150:151] op_sel_hi:[1,0]
	v_mul_f32_e32 v98, 0xbfb8aa3b, v92
	v_mul_f32_e32 v96, 0xbfb8aa3b, v94
	v_mul_f32_e32 v97, 0xbfb8aa3b, v95
	v_mul_f32_e32 v99, 0xbfb8aa3b, v93
	v_exp_f32_e32 v96, v96
	v_exp_f32_e32 v97, v97
	v_exp_f32_e32 v98, v98
	v_exp_f32_e32 v99, v99
	v_add_f32_e32 v96, 1.0, v96
	v_add_f32_e32 v97, 1.0, v97
	v_add_f32_e32 v98, 1.0, v98
	v_add_f32_e32 v99, 1.0, v99
	v_rcp_f32_e32 v96, v96
	v_rcp_f32_e32 v97, v97
	v_rcp_f32_e32 v98, v98
	v_rcp_f32_e32 v99, v99
	v_pk_mul_f32 v[86:87], v[86:87], v[150:151] op_sel_hi:[1,0]
	v_pk_mul_f32 v[84:85], v[84:85], v[150:151] op_sel_hi:[1,0]
	v_pk_mul_f32 v[94:95], v[94:95], v[96:97]
	v_pk_mul_f32 v[92:93], v[92:93], v[98:99]
	v_pk_mul_f32 v[84:85], v[84:85], v[94:95]
	v_pk_mul_f32 v[86:87], v[86:87], v[92:93]
	v_cvt_pk_bf16_f32 v84, v84, v85
	v_cvt_pk_bf16_f32 v85, v86, v87
	v_pk_mul_f32 v[86:87], v[90:91], v[150:151] op_sel_hi:[1,0]
	v_pk_mul_f32 v[88:89], v[88:89], v[150:151] op_sel_hi:[1,0]
	v_mul_f32_e32 v92, 0xbfb8aa3b, v86
	v_mul_f32_e32 v90, 0xbfb8aa3b, v88
	v_mul_f32_e32 v91, 0xbfb8aa3b, v89
	v_mul_f32_e32 v93, 0xbfb8aa3b, v87
	v_exp_f32_e32 v90, v90
	v_exp_f32_e32 v91, v91
	v_exp_f32_e32 v92, v92
	v_exp_f32_e32 v93, v93
	v_add_f32_e32 v90, 1.0, v90
	v_add_f32_e32 v91, 1.0, v91
	v_add_f32_e32 v92, 1.0, v92
	v_add_f32_e32 v93, 1.0, v93
	v_rcp_f32_e32 v90, v90
	v_rcp_f32_e32 v91, v91
	v_rcp_f32_e32 v92, v92
	v_rcp_f32_e32 v93, v93
	v_pk_mul_f32 v[78:79], v[78:79], v[150:151] op_sel_hi:[1,0]
	v_pk_mul_f32 v[76:77], v[76:77], v[150:151] op_sel_hi:[1,0]
	v_pk_mul_f32 v[88:89], v[88:89], v[90:91]
	v_pk_mul_f32 v[86:87], v[86:87], v[92:93]
	v_pk_mul_f32 v[76:77], v[76:77], v[88:89]
	v_pk_mul_f32 v[78:79], v[78:79], v[86:87]
	ds_bpermute_b32 v84, v149, v84
	ds_bpermute_b32 v85, v149, v85
	v_cvt_pk_bf16_f32 v76, v76, v77
	v_cvt_pk_bf16_f32 v77, v78, v79
	ds_bpermute_b32 v76, v149, v76
	ds_bpermute_b32 v77, v149, v77
	v_add_u32_e32 v100, 32, v151
	v_mad_i64_i32 v[78:79], s[22:23], v100, s47, v[136:137]
	v_lshl_add_u64 v[78:79], v[78:79], 0, v[140:141]
	s_waitcnt lgkmcnt(2)
	global_store_dwordx2 v[78:79], v[84:85], off
	s_waitcnt lgkmcnt(0)
	global_store_dwordx2 v[78:79], v[76:77], off offset:32
	v_pk_mul_f32 v[76:77], v[82:83], v[148:149] op_sel_hi:[1,0]
	v_pk_mul_f32 v[78:79], v[80:81], v[148:149] op_sel_hi:[1,0]
	v_mul_f32_e32 v82, 0xbfb8aa3b, v76
	v_mul_f32_e32 v80, 0xbfb8aa3b, v78
	v_mul_f32_e32 v81, 0xbfb8aa3b, v79
	v_mul_f32_e32 v83, 0xbfb8aa3b, v77
	v_exp_f32_e32 v80, v80
	v_exp_f32_e32 v81, v81
	v_exp_f32_e32 v82, v82
	v_exp_f32_e32 v83, v83
	v_add_f32_e32 v80, 1.0, v80
	v_add_f32_e32 v81, 1.0, v81
	v_add_f32_e32 v82, 1.0, v82
	v_add_f32_e32 v83, 1.0, v83
	v_rcp_f32_e32 v80, v80
	v_rcp_f32_e32 v81, v81
	v_rcp_f32_e32 v82, v82
	v_rcp_f32_e32 v83, v83
	v_pk_mul_f32 v[70:71], v[70:71], v[148:149] op_sel_hi:[1,0]
	v_pk_mul_f32 v[68:69], v[68:69], v[148:149] op_sel_hi:[1,0]
	v_pk_mul_f32 v[78:79], v[78:79], v[80:81]
	v_pk_mul_f32 v[76:77], v[76:77], v[82:83]
	v_pk_mul_f32 v[68:69], v[68:69], v[78:79]
	v_pk_mul_f32 v[70:71], v[70:71], v[76:77]
	v_cvt_pk_bf16_f32 v68, v68, v69
	v_cvt_pk_bf16_f32 v69, v70, v71
	v_pk_mul_f32 v[70:71], v[74:75], v[148:149] op_sel_hi:[1,0]
	v_pk_mul_f32 v[72:73], v[72:73], v[148:149] op_sel_hi:[1,0]
	v_mul_f32_e32 v76, 0xbfb8aa3b, v70
	v_mul_f32_e32 v74, 0xbfb8aa3b, v72
	v_mul_f32_e32 v75, 0xbfb8aa3b, v73
	v_mul_f32_e32 v77, 0xbfb8aa3b, v71
	v_exp_f32_e32 v74, v74
	v_exp_f32_e32 v75, v75
	v_exp_f32_e32 v76, v76
	v_exp_f32_e32 v77, v77
	v_add_f32_e32 v74, 1.0, v74
	v_add_f32_e32 v75, 1.0, v75
	v_add_f32_e32 v76, 1.0, v76
	v_add_f32_e32 v77, 1.0, v77
	v_rcp_f32_e32 v74, v74
	v_rcp_f32_e32 v75, v75
	v_rcp_f32_e32 v76, v76
	v_rcp_f32_e32 v77, v77
	v_pk_mul_f32 v[66:67], v[66:67], v[148:149] op_sel_hi:[1,0]
	v_pk_mul_f32 v[64:65], v[64:65], v[148:149] op_sel_hi:[1,0]
	v_pk_mul_f32 v[72:73], v[72:73], v[74:75]
	v_pk_mul_f32 v[70:71], v[70:71], v[76:77]
	v_pk_mul_f32 v[64:65], v[64:65], v[72:73]
	v_pk_mul_f32 v[66:67], v[66:67], v[70:71]
	ds_bpermute_b32 v68, v149, v68
	ds_bpermute_b32 v69, v149, v69
	v_cvt_pk_bf16_f32 v64, v64, v65
	v_cvt_pk_bf16_f32 v65, v66, v67
	ds_bpermute_b32 v64, v149, v64
	ds_bpermute_b32 v65, v149, v65
	v_add_u32_e32 v84, 48, v151
	v_mad_i64_i32 v[66:67], s[22:23], v84, s47, v[136:137]
	v_lshl_add_u64 v[66:67], v[66:67], 0, v[140:141]
	v_pk_mul_f32 v[60:61], v[60:61], v[146:147] op_sel_hi:[1,0]
	s_waitcnt lgkmcnt(2)
	global_store_dwordx2 v[66:67], v[68:69], off
	s_waitcnt lgkmcnt(0)
	global_store_dwordx2 v[66:67], v[64:65], off offset:32
	v_pk_mul_f32 v[62:63], v[62:63], v[146:147] op_sel_hi:[1,0]
	v_mul_f32_e32 v64, 0xbfb8aa3b, v60
	v_mul_f32_e32 v65, 0xbfb8aa3b, v61
	v_exp_f32_e32 v64, v64
	v_exp_f32_e32 v65, v65
	v_mul_f32_e32 v66, 0xbfb8aa3b, v62
	v_mul_f32_e32 v67, 0xbfb8aa3b, v63
	v_exp_f32_e32 v66, v66
	v_exp_f32_e32 v67, v67
	v_add_f32_e32 v64, 1.0, v64
	v_add_f32_e32 v65, 1.0, v65
	v_rcp_f32_e32 v64, v64
	v_rcp_f32_e32 v65, v65
	v_add_f32_e32 v66, 1.0, v66
	v_add_f32_e32 v67, 1.0, v67
	v_rcp_f32_e32 v66, v66
	v_rcp_f32_e32 v67, v67
	v_pk_mul_f32 v[52:53], v[52:53], v[146:147] op_sel_hi:[1,0]
	v_pk_mul_f32 v[60:61], v[60:61], v[64:65]
	v_pk_mul_f32 v[54:55], v[54:55], v[146:147] op_sel_hi:[1,0]
	v_pk_mul_f32 v[52:53], v[52:53], v[60:61]
	v_pk_mul_f32 v[60:61], v[62:63], v[66:67]
	v_cvt_pk_bf16_f32 v52, v52, v53
	v_pk_mul_f32 v[54:55], v[54:55], v[60:61]
	v_pk_mul_f32 v[56:57], v[56:57], v[146:147] op_sel_hi:[1,0]
	v_cvt_pk_bf16_f32 v53, v54, v55
	v_pk_mul_f32 v[54:55], v[58:59], v[146:147] op_sel_hi:[1,0]
	v_mul_f32_e32 v58, 0xbfb8aa3b, v56
	v_mul_f32_e32 v59, 0xbfb8aa3b, v57
	v_mul_f32_e32 v60, 0xbfb8aa3b, v54
	v_mul_f32_e32 v61, 0xbfb8aa3b, v55
	v_exp_f32_e32 v58, v58
	v_exp_f32_e32 v59, v59
	v_exp_f32_e32 v60, v60
	v_exp_f32_e32 v61, v61
	v_add_f32_e32 v58, 1.0, v58
	v_add_f32_e32 v59, 1.0, v59
	v_add_f32_e32 v60, 1.0, v60
	v_add_f32_e32 v61, 1.0, v61
	v_rcp_f32_e32 v58, v58
	v_rcp_f32_e32 v59, v59
	v_rcp_f32_e32 v60, v60
	v_rcp_f32_e32 v61, v61
	v_pk_mul_f32 v[46:47], v[46:47], v[146:147] op_sel_hi:[1,0]
	v_pk_mul_f32 v[44:45], v[44:45], v[146:147] op_sel_hi:[1,0]
	v_pk_mul_f32 v[56:57], v[56:57], v[58:59]
	v_pk_mul_f32 v[54:55], v[54:55], v[60:61]
	v_pk_mul_f32 v[44:45], v[44:45], v[56:57]
	v_pk_mul_f32 v[46:47], v[46:47], v[54:55]
	ds_bpermute_b32 v52, v149, v52
	ds_bpermute_b32 v53, v149, v53
	v_cvt_pk_bf16_f32 v44, v44, v45
	v_cvt_pk_bf16_f32 v45, v46, v47
	ds_bpermute_b32 v44, v149, v44
	ds_bpermute_b32 v45, v149, v45
	v_add_u32_e32 v68, 0x80, v151
	v_mad_i64_i32 v[46:47], s[22:23], v68, s47, v[136:137]
	v_lshl_add_u64 v[46:47], v[46:47], 0, v[140:141]
	s_waitcnt lgkmcnt(2)
	global_store_dwordx2 v[46:47], v[52:53], off
	s_waitcnt lgkmcnt(0)
	global_store_dwordx2 v[46:47], v[44:45], off offset:32
	v_pk_mul_f32 v[44:45], v[50:51], v[144:145] op_sel_hi:[1,0]
	v_pk_mul_f32 v[46:47], v[48:49], v[144:145] op_sel_hi:[1,0]
	v_mul_f32_e32 v50, 0xbfb8aa3b, v44
	v_mul_f32_e32 v48, 0xbfb8aa3b, v46
	v_mul_f32_e32 v49, 0xbfb8aa3b, v47
	v_mul_f32_e32 v51, 0xbfb8aa3b, v45
	v_exp_f32_e32 v48, v48
	v_exp_f32_e32 v49, v49
	v_exp_f32_e32 v50, v50
	v_exp_f32_e32 v51, v51
	v_add_f32_e32 v48, 1.0, v48
	v_add_f32_e32 v49, 1.0, v49
	v_add_f32_e32 v50, 1.0, v50
	v_add_f32_e32 v51, 1.0, v51
	v_rcp_f32_e32 v48, v48
	v_rcp_f32_e32 v49, v49
	v_rcp_f32_e32 v50, v50
	v_rcp_f32_e32 v51, v51
	v_pk_mul_f32 v[38:39], v[38:39], v[144:145] op_sel_hi:[1,0]
	v_pk_mul_f32 v[36:37], v[36:37], v[144:145] op_sel_hi:[1,0]
	v_pk_mul_f32 v[46:47], v[46:47], v[48:49]
	v_pk_mul_f32 v[44:45], v[44:45], v[50:51]
	v_pk_mul_f32 v[36:37], v[36:37], v[46:47]
	v_pk_mul_f32 v[38:39], v[38:39], v[44:45]
	v_cvt_pk_bf16_f32 v36, v36, v37
	v_cvt_pk_bf16_f32 v37, v38, v39
	v_pk_mul_f32 v[38:39], v[42:43], v[144:145] op_sel_hi:[1,0]
	v_pk_mul_f32 v[40:41], v[40:41], v[144:145] op_sel_hi:[1,0]
	v_mul_f32_e32 v44, 0xbfb8aa3b, v38
	v_mul_f32_e32 v42, 0xbfb8aa3b, v40
	v_mul_f32_e32 v43, 0xbfb8aa3b, v41
	v_mul_f32_e32 v45, 0xbfb8aa3b, v39
	v_exp_f32_e32 v42, v42
	v_exp_f32_e32 v43, v43
	v_exp_f32_e32 v44, v44
	v_exp_f32_e32 v45, v45
	v_add_f32_e32 v42, 1.0, v42
	v_add_f32_e32 v43, 1.0, v43
	v_add_f32_e32 v44, 1.0, v44
	v_add_f32_e32 v45, 1.0, v45
	v_rcp_f32_e32 v42, v42
	v_rcp_f32_e32 v43, v43
	v_rcp_f32_e32 v44, v44
	v_rcp_f32_e32 v45, v45
	v_pk_mul_f32 v[30:31], v[30:31], v[144:145] op_sel_hi:[1,0]
	v_pk_mul_f32 v[28:29], v[28:29], v[144:145] op_sel_hi:[1,0]
	v_pk_mul_f32 v[40:41], v[40:41], v[42:43]
	v_pk_mul_f32 v[38:39], v[38:39], v[44:45]
	v_pk_mul_f32 v[28:29], v[28:29], v[40:41]
	v_pk_mul_f32 v[30:31], v[30:31], v[38:39]
	ds_bpermute_b32 v36, v149, v36
	ds_bpermute_b32 v37, v149, v37
	v_cvt_pk_bf16_f32 v28, v28, v29
	v_cvt_pk_bf16_f32 v29, v30, v31
	ds_bpermute_b32 v28, v149, v28
	ds_bpermute_b32 v29, v149, v29
	v_add_u32_e32 v52, 0x90, v151
	v_mad_i64_i32 v[30:31], s[22:23], v52, s47, v[136:137]
	v_lshl_add_u64 v[30:31], v[30:31], 0, v[140:141]
	s_waitcnt lgkmcnt(2)
	global_store_dwordx2 v[30:31], v[36:37], off
	s_waitcnt lgkmcnt(0)
	global_store_dwordx2 v[30:31], v[28:29], off offset:32
	v_pk_mul_f32 v[28:29], v[34:35], v[142:143] op_sel_hi:[1,0]
	v_pk_mul_f32 v[30:31], v[32:33], v[142:143] op_sel_hi:[1,0]
	v_mul_f32_e32 v34, 0xbfb8aa3b, v28
	v_mul_f32_e32 v32, 0xbfb8aa3b, v30
	v_mul_f32_e32 v33, 0xbfb8aa3b, v31
	v_mul_f32_e32 v35, 0xbfb8aa3b, v29
	v_exp_f32_e32 v32, v32
	v_exp_f32_e32 v33, v33
	v_exp_f32_e32 v34, v34
	v_exp_f32_e32 v35, v35
	v_add_f32_e32 v32, 1.0, v32
	v_add_f32_e32 v33, 1.0, v33
	v_add_f32_e32 v34, 1.0, v34
	v_add_f32_e32 v35, 1.0, v35
	v_rcp_f32_e32 v32, v32
	v_rcp_f32_e32 v33, v33
	v_rcp_f32_e32 v34, v34
	v_rcp_f32_e32 v35, v35
	v_pk_mul_f32 v[22:23], v[22:23], v[142:143] op_sel_hi:[1,0]
	v_pk_mul_f32 v[20:21], v[20:21], v[142:143] op_sel_hi:[1,0]
	v_pk_mul_f32 v[30:31], v[30:31], v[32:33]
	v_pk_mul_f32 v[28:29], v[28:29], v[34:35]
	v_pk_mul_f32 v[20:21], v[20:21], v[30:31]
	v_pk_mul_f32 v[22:23], v[22:23], v[28:29]
	v_cvt_pk_bf16_f32 v20, v20, v21
	v_cvt_pk_bf16_f32 v21, v22, v23
	v_pk_mul_f32 v[22:23], v[26:27], v[142:143] op_sel_hi:[1,0]
	v_pk_mul_f32 v[24:25], v[24:25], v[142:143] op_sel_hi:[1,0]
	v_mul_f32_e32 v28, 0xbfb8aa3b, v22
	v_mul_f32_e32 v26, 0xbfb8aa3b, v24
	v_mul_f32_e32 v27, 0xbfb8aa3b, v25
	v_mul_f32_e32 v29, 0xbfb8aa3b, v23
	v_exp_f32_e32 v26, v26
	v_exp_f32_e32 v27, v27
	v_exp_f32_e32 v28, v28
	v_exp_f32_e32 v29, v29
	v_add_f32_e32 v26, 1.0, v26
	v_add_f32_e32 v27, 1.0, v27
	v_add_f32_e32 v28, 1.0, v28
	v_add_f32_e32 v29, 1.0, v29
	v_rcp_f32_e32 v26, v26
	v_rcp_f32_e32 v27, v27
	v_rcp_f32_e32 v28, v28
	v_rcp_f32_e32 v29, v29
	v_pk_mul_f32 v[14:15], v[14:15], v[142:143] op_sel_hi:[1,0]
	v_pk_mul_f32 v[12:13], v[12:13], v[142:143] op_sel_hi:[1,0]
	v_pk_mul_f32 v[24:25], v[24:25], v[26:27]
	v_pk_mul_f32 v[22:23], v[22:23], v[28:29]
	v_pk_mul_f32 v[12:13], v[12:13], v[24:25]
	v_pk_mul_f32 v[14:15], v[14:15], v[22:23]
	ds_bpermute_b32 v20, v149, v20
	ds_bpermute_b32 v21, v149, v21
	v_cvt_pk_bf16_f32 v12, v12, v13
	v_cvt_pk_bf16_f32 v13, v14, v15
	ds_bpermute_b32 v12, v149, v12
	ds_bpermute_b32 v13, v149, v13
	v_add_u32_e32 v36, 0xa0, v151
	v_mad_i64_i32 v[14:15], s[22:23], v36, s47, v[136:137]
	v_lshl_add_u64 v[14:15], v[14:15], 0, v[140:141]
	s_waitcnt lgkmcnt(2)
	global_store_dwordx2 v[14:15], v[20:21], off
	s_waitcnt lgkmcnt(0)
	global_store_dwordx2 v[14:15], v[12:13], off offset:32
	v_pk_mul_f32 v[12:13], v[18:19], v[138:139] op_sel_hi:[1,0]
	v_pk_mul_f32 v[14:15], v[16:17], v[138:139] op_sel_hi:[1,0]
	v_mul_f32_e32 v18, 0xbfb8aa3b, v12
	v_mul_f32_e32 v16, 0xbfb8aa3b, v14
	v_mul_f32_e32 v17, 0xbfb8aa3b, v15
	v_mul_f32_e32 v19, 0xbfb8aa3b, v13
	v_exp_f32_e32 v16, v16
	v_exp_f32_e32 v17, v17
	v_exp_f32_e32 v18, v18
	v_exp_f32_e32 v19, v19
	v_add_f32_e32 v16, 1.0, v16
	v_add_f32_e32 v17, 1.0, v17
	v_add_f32_e32 v18, 1.0, v18
	v_add_f32_e32 v19, 1.0, v19
	v_rcp_f32_e32 v16, v16
	v_rcp_f32_e32 v17, v17
	v_rcp_f32_e32 v18, v18
	v_rcp_f32_e32 v19, v19
	v_pk_mul_f32 v[6:7], v[6:7], v[138:139] op_sel_hi:[1,0]
	v_pk_mul_f32 v[4:5], v[4:5], v[138:139] op_sel_hi:[1,0]
	v_pk_mul_f32 v[14:15], v[14:15], v[16:17]
	v_pk_mul_f32 v[12:13], v[12:13], v[18:19]
	v_pk_mul_f32 v[4:5], v[4:5], v[14:15]
	v_pk_mul_f32 v[6:7], v[6:7], v[12:13]
	v_cvt_pk_bf16_f32 v4, v4, v5
	v_cvt_pk_bf16_f32 v5, v6, v7
	v_pk_mul_f32 v[6:7], v[10:11], v[138:139] op_sel_hi:[1,0]
	v_pk_mul_f32 v[8:9], v[8:9], v[138:139] op_sel_hi:[1,0]
	v_mul_f32_e32 v12, 0xbfb8aa3b, v6
	v_mul_f32_e32 v10, 0xbfb8aa3b, v8
	v_mul_f32_e32 v11, 0xbfb8aa3b, v9
	v_mul_f32_e32 v13, 0xbfb8aa3b, v7
	v_exp_f32_e32 v10, v10
	v_exp_f32_e32 v11, v11
	v_exp_f32_e32 v12, v12
	v_exp_f32_e32 v13, v13
	v_add_f32_e32 v10, 1.0, v10
	v_add_f32_e32 v11, 1.0, v11
	v_add_f32_e32 v12, 1.0, v12
	v_add_f32_e32 v13, 1.0, v13
	v_rcp_f32_e32 v10, v10
	v_rcp_f32_e32 v11, v11
	v_rcp_f32_e32 v12, v12
	v_rcp_f32_e32 v13, v13
	v_pk_mul_f32 v[2:3], v[2:3], v[138:139] op_sel_hi:[1,0]
	v_pk_mul_f32 v[0:1], v[0:1], v[138:139] op_sel_hi:[1,0]
	v_pk_mul_f32 v[8:9], v[8:9], v[10:11]
	v_pk_mul_f32 v[6:7], v[6:7], v[12:13]
	v_pk_mul_f32 v[0:1], v[0:1], v[8:9]
	v_pk_mul_f32 v[2:3], v[2:3], v[6:7]
	ds_bpermute_b32 v4, v149, v4
	ds_bpermute_b32 v5, v149, v5
	v_cvt_pk_bf16_f32 v0, v0, v1
	v_cvt_pk_bf16_f32 v1, v2, v3
	ds_bpermute_b32 v0, v149, v0
	ds_bpermute_b32 v1, v149, v1
	v_add_u32_e32 v20, 0xb0, v151
	v_mad_i64_i32 v[2:3], s[22:23], v20, s47, v[136:137]
	v_lshl_add_u64 v[2:3], v[2:3], 0, v[140:141]
	s_mov_b64 s[22:23], s[16:17]
	s_waitcnt lgkmcnt(2)
	global_store_dwordx2 v[2:3], v[4:5], off
	s_waitcnt lgkmcnt(0)
	global_store_dwordx2 v[2:3], v[0:1], off offset:32
	s_cbranch_vccz .LBB0_1164
	s_waitcnt vmcnt(0)
	s_cmpk_gt_u32 s28, 0xff
	s_cbranch_scc1 .LBB0_1171
	s_barrier

.LBB0_1258:
	ds_read_b128 v[128:131], v159
	ds_read_b128 v[132:135], v159 offset:1024
	ds_read_b128 v[136:139], v159 offset:2048
	ds_read_b128 v[150:153], v159 offset:3072
	s_add_i32 s54, s18, 2
	s_add_u32 s19, s16, 0xffea0080
	s_addc_u32 s20, s17, -1
	s_cmp_eq_u32 s13, s18
	s_cselect_b32 s18, s4, s52
	s_cselect_b32 s21, s15, s20
	s_cselect_b32 s20, s14, s19
	s_cselect_b32 s19, s5, s53
	v_lshl_add_u64 v[166:167], s[16:17], 0, v[146:147]
	s_add_i32 m0, s26, 0xc000
	ds_read_b128 v[154:157], v160
	ds_read_b128 v[162:165], v160 offset:1024
	ds_read_b128 v[172:175], v160 offset:2048
	ds_read_b128 v[176:179], v160 offset:3072
	ds_read_b128 v[180:183], v160 offset:4096
	ds_read_b128 v[184:187], v160 offset:5120
	ds_read_b128 v[188:191], v160 offset:6144
	ds_read_b128 v[192:195], v160 offset:7168
	global_load_lds_dwordx4 v[166:167], off
	v_lshl_add_u64 v[166:167], s[16:17], 0, v[148:149]
	s_add_i32 m0, s26, 0xe000
	s_nop 0
	global_load_lds_dwordx4 v[166:167], off
	s_waitcnt lgkmcnt(8)
	s_barrier
	s_waitcnt lgkmcnt(0)


	v_mfma_f32_16x16x32_bf16 v[124:127], v[128:131], v[154:157], v[124:127]
	v_mfma_f32_16x16x32_bf16 v[120:123], v[136:139], v[154:157], v[120:123]
	v_mfma_f32_16x16x32_bf16 v[116:119], v[128:131], v[172:175], v[116:119]
	v_mfma_f32_16x16x32_bf16 v[104:107], v[136:139], v[172:175], v[104:107]
	v_mfma_f32_16x16x32_bf16 v[96:99], v[128:131], v[180:183], v[96:99]
	v_mfma_f32_16x16x32_bf16 v[88:91], v[136:139], v[180:183], v[88:91]
	v_mfma_f32_16x16x32_bf16 v[80:83], v[128:131], v[188:191], v[80:83]
	v_mfma_f32_16x16x32_bf16 v[72:75], v[136:139], v[188:191], v[72:75]
	v_mfma_f32_16x16x32_bf16 v[124:127], v[132:135], v[162:165], v[124:127]
	v_mfma_f32_16x16x32_bf16 v[120:123], v[150:153], v[162:165], v[120:123]
	v_mfma_f32_16x16x32_bf16 v[116:119], v[132:135], v[176:179], v[116:119]
	v_mfma_f32_16x16x32_bf16 v[104:107], v[150:153], v[176:179], v[104:107]
	v_mfma_f32_16x16x32_bf16 v[96:99], v[132:135], v[184:187], v[96:99]
	v_mfma_f32_16x16x32_bf16 v[88:91], v[150:153], v[184:187], v[88:91]
	v_mfma_f32_16x16x32_bf16 v[80:83], v[132:135], v[192:195], v[80:83]
	v_mfma_f32_16x16x32_bf16 v[72:75], v[150:153], v[192:195], v[72:75]

	s_barrier
	s_add_i32 s55, s35, s25
	v_lshl_add_u64 v[166:167], s[18:19], 0, v[140:141]
	s_mov_b32 m0, s55
	ds_read_b128 v[196:199], v161
	ds_read_b128 v[200:203], v161 offset:1024
	ds_read_b128 v[204:207], v161 offset:2048
	ds_read_b128 v[212:215], v161 offset:3072
	global_load_lds_dwordx4 v[166:167], off
	v_lshl_add_u64 v[208:209], s[18:19], 0, v[142:143]
	s_add_i32 m0, s55, 0x2000
	s_nop 0
	global_load_lds_dwordx4 v[208:209], off
	s_barrier
	s_waitcnt lgkmcnt(0)


	v_mfma_f32_16x16x32_bf16 v[112:115], v[196:199], v[154:157], v[112:115]
	v_mfma_f32_16x16x32_bf16 v[108:111], v[204:207], v[154:157], v[108:111]
	v_mfma_f32_16x16x32_bf16 v[100:103], v[196:199], v[172:175], v[100:103]
	v_mfma_f32_16x16x32_bf16 v[92:95], v[204:207], v[172:175], v[92:95]
	v_mfma_f32_16x16x32_bf16 v[84:87], v[196:199], v[180:183], v[84:87]
	v_mfma_f32_16x16x32_bf16 v[76:79], v[204:207], v[180:183], v[76:79]
	v_mfma_f32_16x16x32_bf16 v[68:71], v[196:199], v[188:191], v[68:71]
	v_mfma_f32_16x16x32_bf16 v[64:67], v[204:207], v[188:191], v[64:67]
	v_mfma_f32_16x16x32_bf16 v[112:115], v[200:203], v[162:165], v[112:115]
	v_mfma_f32_16x16x32_bf16 v[108:111], v[212:215], v[162:165], v[108:111]
	v_mfma_f32_16x16x32_bf16 v[100:103], v[200:203], v[176:179], v[100:103]
	v_mfma_f32_16x16x32_bf16 v[92:95], v[212:215], v[176:179], v[92:95]
	v_mfma_f32_16x16x32_bf16 v[84:87], v[200:203], v[184:187], v[84:87]
	v_mfma_f32_16x16x32_bf16 v[76:79], v[212:215], v[184:187], v[76:79]
	v_mfma_f32_16x16x32_bf16 v[68:71], v[200:203], v[192:195], v[68:71]
	v_mfma_f32_16x16x32_bf16 v[64:67], v[212:215], v[192:195], v[64:67]

	s_mov_b32 m0, s26
	v_lshl_add_u64 v[216:217], s[20:21], 0, v[140:141]
	s_barrier
	ds_read_b128 v[154:157], v160 offset:16384
	ds_read_b128 v[162:165], v160 offset:17408
	ds_read_b128 v[172:175], v160 offset:18432
	ds_read_b128 v[176:179], v160 offset:19456
	ds_read_b128 v[180:183], v160 offset:20480
	ds_read_b128 v[184:187], v160 offset:21504
	ds_read_b128 v[188:191], v160 offset:22528
	ds_read_b128 v[192:195], v160 offset:23552
	global_load_lds_dwordx4 v[216:217], off
	v_lshl_add_u64 v[218:219], s[20:21], 0, v[142:143]
	s_mov_b32 m0, s27
	s_nop 0
	global_load_lds_dwordx4 v[218:219], off
	s_barrier
	s_waitcnt lgkmcnt(0)


	v_mfma_f32_16x16x32_bf16 v[60:63], v[128:131], v[154:157], v[60:63]
	v_mfma_f32_16x16x32_bf16 v[56:59], v[136:139], v[154:157], v[56:59]
	v_mfma_f32_16x16x32_bf16 v[52:55], v[128:131], v[172:175], v[52:55]
	v_mfma_f32_16x16x32_bf16 v[40:43], v[136:139], v[172:175], v[40:43]
	v_mfma_f32_16x16x32_bf16 v[36:39], v[128:131], v[180:183], v[36:39]
	v_mfma_f32_16x16x32_bf16 v[24:27], v[136:139], v[180:183], v[24:27]
	v_mfma_f32_16x16x32_bf16 v[20:23], v[128:131], v[188:191], v[20:23]
	v_mfma_f32_16x16x32_bf16 v[8:11], v[136:139], v[188:191], v[8:11]
	v_mfma_f32_16x16x32_bf16 v[60:63], v[132:135], v[162:165], v[60:63]
	v_mfma_f32_16x16x32_bf16 v[56:59], v[150:153], v[162:165], v[56:59]
	v_mfma_f32_16x16x32_bf16 v[52:55], v[132:135], v[176:179], v[52:55]
	v_mfma_f32_16x16x32_bf16 v[40:43], v[150:153], v[176:179], v[40:43]
	v_mfma_f32_16x16x32_bf16 v[36:39], v[132:135], v[184:187], v[36:39]
	v_mfma_f32_16x16x32_bf16 v[24:27], v[150:153], v[184:187], v[24:27]
	v_mfma_f32_16x16x32_bf16 v[20:23], v[132:135], v[192:195], v[20:23]
	v_mfma_f32_16x16x32_bf16 v[8:11], v[150:153], v[192:195], v[8:11]

	s_barrier
	s_add_u32 s56, s18, 0x160000
	s_addc_u32 s57, s19, 0
	s_add_i32 s55, s36, s25
	v_lshl_add_u64 v[128:129], s[56:57], 0, v[140:141]
	s_mov_b32 m0, s55
	s_nop 0
	global_load_lds_dwordx4 v[128:129], off
	v_lshl_add_u64 v[128:129], s[56:57], 0, v[142:143]
	s_add_i32 m0, s55, 0x2000
	s_nop 0
	global_load_lds_dwordx4 v[128:129], off
	s_waitcnt vmcnt(6)
	s_barrier

	v_mfma_f32_16x16x32_bf16 v[48:51], v[196:199], v[154:157], v[48:51]
	v_mfma_f32_16x16x32_bf16 v[44:47], v[204:207], v[154:157], v[44:47]
	v_mfma_f32_16x16x32_bf16 v[32:35], v[196:199], v[172:175], v[32:35]
	v_mfma_f32_16x16x32_bf16 v[28:31], v[204:207], v[172:175], v[28:31]
	v_mfma_f32_16x16x32_bf16 v[16:19], v[196:199], v[180:183], v[16:19]
	v_mfma_f32_16x16x32_bf16 v[12:15], v[204:207], v[180:183], v[12:15]
	v_mfma_f32_16x16x32_bf16 v[4:7], v[196:199], v[188:191], v[4:7]
	v_mfma_f32_16x16x32_bf16 v[0:3], v[204:207], v[188:191], v[0:3]
	v_mfma_f32_16x16x32_bf16 v[48:51], v[200:203], v[162:165], v[48:51]
	v_mfma_f32_16x16x32_bf16 v[44:47], v[212:215], v[162:165], v[44:47]
	v_mfma_f32_16x16x32_bf16 v[32:35], v[200:203], v[176:179], v[32:35]
	v_mfma_f32_16x16x32_bf16 v[28:31], v[212:215], v[176:179], v[28:31]
	v_mfma_f32_16x16x32_bf16 v[16:19], v[200:203], v[184:187], v[16:19]
	v_mfma_f32_16x16x32_bf16 v[12:15], v[212:215], v[184:187], v[12:15]
	v_mfma_f32_16x16x32_bf16 v[4:7], v[200:203], v[192:195], v[4:7]
	v_mfma_f32_16x16x32_bf16 v[0:3], v[212:215], v[192:195], v[0:3]

	s_add_i32 s55, 0, 0x18000
	v_add_u32_e32 v144, s55, v158
	s_barrier
	ds_read_b128 v[128:131], v144
	ds_read_b128 v[132:135], v144 offset:1024
	ds_read_b128 v[136:139], v144 offset:2048
	ds_read_b128 v[150:153], v144 offset:3072
	s_add_u32 s20, s20, 0x160000
	s_addc_u32 s21, s21, 0
	s_mov_b32 m0, s28
	v_lshl_add_u64 v[196:197], s[20:21], 0, v[140:141]
	ds_read_b128 v[154:157], v160 offset:32768
	ds_read_b128 v[162:165], v160 offset:33792
	ds_read_b128 v[172:175], v160 offset:34816
	ds_read_b128 v[176:179], v160 offset:35840
	ds_read_b128 v[180:183], v160 offset:36864
	ds_read_b128 v[184:187], v160 offset:37888
	ds_read_b128 v[188:191], v160 offset:38912
	ds_read_b128 v[192:195], v160 offset:39936
	global_load_lds_dwordx4 v[196:197], off
	v_lshl_add_u64 v[196:197], s[20:21], 0, v[142:143]
	s_mov_b32 m0, s29
	s_nop 0
	global_load_lds_dwordx4 v[196:197], off
	s_waitcnt lgkmcnt(8)
	s_barrier
	s_waitcnt lgkmcnt(0)


	v_mfma_f32_16x16x32_bf16 v[124:127], v[128:131], v[154:157], v[124:127]
	v_mfma_f32_16x16x32_bf16 v[120:123], v[136:139], v[154:157], v[120:123]
	v_mfma_f32_16x16x32_bf16 v[116:119], v[128:131], v[172:175], v[116:119]
	v_mfma_f32_16x16x32_bf16 v[104:107], v[136:139], v[172:175], v[104:107]
	v_mfma_f32_16x16x32_bf16 v[96:99], v[128:131], v[180:183], v[96:99]
	v_mfma_f32_16x16x32_bf16 v[88:91], v[136:139], v[180:183], v[88:91]
	v_mfma_f32_16x16x32_bf16 v[80:83], v[128:131], v[188:191], v[80:83]
	v_mfma_f32_16x16x32_bf16 v[72:75], v[136:139], v[188:191], v[72:75]
	v_mfma_f32_16x16x32_bf16 v[124:127], v[132:135], v[162:165], v[124:127]
	v_mfma_f32_16x16x32_bf16 v[120:123], v[150:153], v[162:165], v[120:123]
	v_mfma_f32_16x16x32_bf16 v[116:119], v[132:135], v[176:179], v[116:119]
	v_mfma_f32_16x16x32_bf16 v[104:107], v[150:153], v[176:179], v[104:107]
	v_mfma_f32_16x16x32_bf16 v[96:99], v[132:135], v[184:187], v[96:99]
	v_mfma_f32_16x16x32_bf16 v[88:91], v[150:153], v[184:187], v[88:91]
	v_mfma_f32_16x16x32_bf16 v[80:83], v[132:135], v[192:195], v[80:83]
	v_mfma_f32_16x16x32_bf16 v[72:75], v[150:153], v[192:195], v[72:75]

	s_barrier
	s_add_i32 s20, 0, 0x1c000
	s_add_i32 s21, s55, s25
	v_add_u32_e32 v144, s20, v158
	v_lshl_add_u64 v[166:167], v[166:167], 0, s[6:7]
	s_mov_b32 m0, s21
	ds_read_b128 v[196:199], v144
	ds_read_b128 v[200:203], v144 offset:1024
	ds_read_b128 v[204:207], v144 offset:2048
	ds_read_b128 v[212:215], v144 offset:3072
	global_load_lds_dwordx4 v[166:167], off
	v_lshl_add_u64 v[166:167], v[208:209], 0, s[6:7]
	s_add_i32 m0, s21, 0x2000
	s_nop 0
	global_load_lds_dwordx4 v[166:167], off
	s_barrier
	s_waitcnt lgkmcnt(0)


	v_mfma_f32_16x16x32_bf16 v[112:115], v[196:199], v[154:157], v[112:115]
	v_mfma_f32_16x16x32_bf16 v[108:111], v[204:207], v[154:157], v[108:111]
	v_mfma_f32_16x16x32_bf16 v[100:103], v[196:199], v[172:175], v[100:103]
	v_mfma_f32_16x16x32_bf16 v[92:95], v[204:207], v[172:175], v[92:95]
	v_mfma_f32_16x16x32_bf16 v[84:87], v[196:199], v[180:183], v[84:87]
	v_mfma_f32_16x16x32_bf16 v[76:79], v[204:207], v[180:183], v[76:79]
	v_mfma_f32_16x16x32_bf16 v[68:71], v[196:199], v[188:191], v[68:71]
	v_mfma_f32_16x16x32_bf16 v[64:67], v[204:207], v[188:191], v[64:67]
	v_mfma_f32_16x16x32_bf16 v[112:115], v[200:203], v[162:165], v[112:115]
	v_mfma_f32_16x16x32_bf16 v[108:111], v[212:215], v[162:165], v[108:111]
	v_mfma_f32_16x16x32_bf16 v[100:103], v[200:203], v[176:179], v[100:103]
	v_mfma_f32_16x16x32_bf16 v[92:95], v[212:215], v[176:179], v[92:95]
	v_mfma_f32_16x16x32_bf16 v[84:87], v[200:203], v[184:187], v[84:87]
	v_mfma_f32_16x16x32_bf16 v[76:79], v[212:215], v[184:187], v[76:79]
	v_mfma_f32_16x16x32_bf16 v[68:71], v[200:203], v[192:195], v[68:71]
	v_mfma_f32_16x16x32_bf16 v[64:67], v[212:215], v[192:195], v[64:67]

	s_mov_b32 m0, s33
	v_lshl_add_u64 v[166:167], v[216:217], 0, s[6:7]
	s_barrier
	ds_read_b128 v[154:157], v160 offset:49152
	ds_read_b128 v[162:165], v160 offset:50176
	ds_read_b128 v[172:175], v160 offset:51200
	ds_read_b128 v[176:179], v160 offset:52224
	ds_read_b128 v[180:183], v160 offset:53248
	ds_read_b128 v[184:187], v160 offset:54272
	ds_read_b128 v[188:191], v160 offset:55296
	ds_read_b128 v[192:195], v160 offset:56320
	global_load_lds_dwordx4 v[166:167], off
	v_lshl_add_u64 v[166:167], v[218:219], 0, s[6:7]
	s_mov_b32 m0, s34
	s_nop 0
	global_load_lds_dwordx4 v[166:167], off
	s_barrier
	s_waitcnt lgkmcnt(0)


	v_mfma_f32_16x16x32_bf16 v[60:63], v[128:131], v[154:157], v[60:63]
	v_mfma_f32_16x16x32_bf16 v[56:59], v[136:139], v[154:157], v[56:59]
	v_mfma_f32_16x16x32_bf16 v[52:55], v[128:131], v[172:175], v[52:55]
	v_mfma_f32_16x16x32_bf16 v[40:43], v[136:139], v[172:175], v[40:43]
	v_mfma_f32_16x16x32_bf16 v[36:39], v[128:131], v[180:183], v[36:39]
	v_mfma_f32_16x16x32_bf16 v[24:27], v[136:139], v[180:183], v[24:27]
	v_mfma_f32_16x16x32_bf16 v[20:23], v[128:131], v[188:191], v[20:23]
	v_mfma_f32_16x16x32_bf16 v[8:11], v[136:139], v[188:191], v[8:11]
	v_mfma_f32_16x16x32_bf16 v[60:63], v[132:135], v[162:165], v[60:63]
	v_mfma_f32_16x16x32_bf16 v[56:59], v[150:153], v[162:165], v[56:59]
	v_mfma_f32_16x16x32_bf16 v[52:55], v[132:135], v[176:179], v[52:55]
	v_mfma_f32_16x16x32_bf16 v[40:43], v[150:153], v[176:179], v[40:43]
	v_mfma_f32_16x16x32_bf16 v[36:39], v[132:135], v[184:187], v[36:39]
	v_mfma_f32_16x16x32_bf16 v[24:27], v[150:153], v[184:187], v[24:27]
	v_mfma_f32_16x16x32_bf16 v[20:23], v[132:135], v[192:195], v[20:23]
	v_mfma_f32_16x16x32_bf16 v[8:11], v[150:153], v[192:195], v[8:11]

	s_barrier
	s_add_u32 s18, s18, 0x160080
	s_addc_u32 s19, s19, 0
	s_add_i32 s20, s20, s25
	v_lshl_add_u64 v[128:129], s[18:19], 0, v[140:141]
	s_mov_b32 m0, s20
	s_nop 0
	global_load_lds_dwordx4 v[128:129], off
	v_lshl_add_u64 v[128:129], s[18:19], 0, v[142:143]
	s_add_i32 m0, s20, 0x2000
	s_nop 0
	global_load_lds_dwordx4 v[128:129], off
	s_waitcnt vmcnt(6)
	s_barrier

	v_mfma_f32_16x16x32_bf16 v[48:51], v[196:199], v[154:157], v[48:51]
	v_mfma_f32_16x16x32_bf16 v[44:47], v[204:207], v[154:157], v[44:47]
	v_mfma_f32_16x16x32_bf16 v[32:35], v[196:199], v[172:175], v[32:35]
	v_mfma_f32_16x16x32_bf16 v[28:31], v[204:207], v[172:175], v[28:31]
	v_mfma_f32_16x16x32_bf16 v[16:19], v[196:199], v[180:183], v[16:19]
	v_mfma_f32_16x16x32_bf16 v[12:15], v[204:207], v[180:183], v[12:15]
	v_mfma_f32_16x16x32_bf16 v[4:7], v[196:199], v[188:191], v[4:7]
	v_mfma_f32_16x16x32_bf16 v[0:3], v[204:207], v[188:191], v[0:3]
	v_mfma_f32_16x16x32_bf16 v[48:51], v[200:203], v[162:165], v[48:51]
	v_mfma_f32_16x16x32_bf16 v[44:47], v[212:215], v[162:165], v[44:47]
	v_mfma_f32_16x16x32_bf16 v[32:35], v[200:203], v[176:179], v[32:35]
	v_mfma_f32_16x16x32_bf16 v[28:31], v[212:215], v[176:179], v[28:31]
	v_mfma_f32_16x16x32_bf16 v[16:19], v[200:203], v[184:187], v[16:19]
	v_mfma_f32_16x16x32_bf16 v[12:15], v[212:215], v[184:187], v[12:15]
	v_mfma_f32_16x16x32_bf16 v[4:7], v[200:203], v[192:195], v[4:7]
	v_mfma_f32_16x16x32_bf16 v[0:3], v[212:215], v[192:195], v[0:3]

	s_add_u32 s16, s16, 0x100
	s_addc_u32 s17, s17, 0
	s_add_u32 s52, s52, 0x100
	s_addc_u32 s53, s53, 0
	s_cmp_ge_i32 s54, s51
	s_mov_b32 s18, s54
	s_barrier
	s_cbranch_scc0 .LBB0_1258
	v_mov_b32_e32 v128, v210
	v_mov_b32_e32 v129, v169
	s_mov_b64 s[16:17], -1
	v_lshl_add_u32 v128, v128, 4, v129
	v_ashrrev_i32_e32 v150, 2, v128
	v_and_b32_e32 v129, 3, v129
	v_and_b32_e32 v128, -4, v128
	v_lshl_add_u32 v162, v129, 6, v128
	s_cmp_lt_i32 s2, 0
	v_lshlrev_b32_e32 v144, 4, v129
	s_cbranch_scc0 .LBB0_1261
	s_lshl_b32 s13, s50, 8
	s_add_i32 s13, s13, s30
	v_add_u32_e32 v128, s13, v150
	v_ashrrev_i32_e32 v129, 31, v128
	v_readlane_b32 s52, v254, 22
	v_lshlrev_b64 v[128:129], 13, v[128:129]
	v_readlane_b32 s66, v254, 36
	v_readlane_b32 s67, v254, 37
	s_lshl_b32 s16, s49, 8
	s_ashr_i32 s17, s16, 31
	v_lshl_add_u64 v[128:129], s[66:67], 0, v[128:129]
	v_lshl_add_u64 v[128:129], s[16:17], 2, v[128:129]
	s_lshl_b32 s16, s31, 2
	s_mov_b32 s17, s3
	v_lshl_add_u64 v[128:129], v[128:129], 0, s[16:17]
	v_lshl_add_u64 v[152:153], v[128:129], 0, v[144:145]
	global_load_dwordx4 v[164:167], v[152:153], off
	global_load_dwordx4 v[172:175], v[152:153], off offset:64
	global_load_dwordx4 v[176:179], v[152:153], off offset:512
	global_load_dwordx4 v[180:183], v[152:153], off offset:576
	v_add_co_u32_e32 v136, vcc, s37, v152
	ds_bpermute_b32 v138, v162, v124
	s_nop 0
	v_addc_co_u32_e32 v137, vcc, 0, v153, vcc
	global_load_dwordx4 v[184:187], v[136:137], off
	global_load_dwordx4 v[188:191], v[136:137], off offset:64
	global_load_dwordx4 v[192:195], v[136:137], off offset:512
	global_load_dwordx4 v[132:135], v[136:137], off offset:576
	v_add_co_u32_e32 v208, vcc, s38, v152
	ds_bpermute_b32 v139, v162, v125
	s_nop 0
	v_addc_co_u32_e32 v209, vcc, 0, v153, vcc
	global_load_dwordx4 v[196:199], v[208:209], off
	global_load_dwordx4 v[200:203], v[208:209], off offset:64
	global_load_dwordx4 v[204:207], v[208:209], off offset:512
	global_load_dwordx4 v[212:215], v[208:209], off offset:576
	v_add_co_u32_e32 v154, vcc, s39, v152
	ds_bpermute_b32 v156, v162, v126
	s_nop 0
	v_addc_co_u32_e32 v155, vcc, 0, v153, vcc
	global_load_dwordx4 v[216:219], v[154:155], off
	global_load_dwordx4 v[220:223], v[154:155], off offset:64
	global_load_dwordx4 v[224:227], v[154:155], off offset:512
	global_load_dwordx4 v[128:131], v[154:155], off offset:576
	ds_bpermute_b32 v157, v162, v127
	ds_bpermute_b32 v228, v162, v120
	ds_bpermute_b32 v229, v162, v121
	ds_bpermute_b32 v230, v162, v122
	ds_bpermute_b32 v231, v162, v123
	ds_bpermute_b32 v232, v162, v112
	ds_bpermute_b32 v233, v162, v113
	ds_bpermute_b32 v234, v162, v114
	ds_bpermute_b32 v235, v162, v115
	ds_bpermute_b32 v236, v162, v108
	ds_bpermute_b32 v237, v162, v109
	ds_bpermute_b32 v238, v162, v110
	ds_bpermute_b32 v239, v162, v111
	ds_bpermute_b32 v240, v162, v116
	ds_bpermute_b32 v241, v162, v117
	ds_bpermute_b32 v242, v162, v118
	ds_bpermute_b32 v243, v162, v119
	ds_bpermute_b32 v244, v162, v104
	ds_bpermute_b32 v245, v162, v105
	ds_bpermute_b32 v246, v162, v106
	ds_bpermute_b32 v247, v162, v107
	ds_bpermute_b32 v248, v162, v100
	ds_bpermute_b32 v249, v162, v101
	ds_bpermute_b32 v250, v162, v102
	ds_bpermute_b32 v251, v162, v103
	ds_bpermute_b32 v252, v162, v94
	ds_bpermute_b32 v253, v162, v95
	v_readlane_b32 s53, v254, 23
	v_readlane_b32 s54, v254, 24
	v_readlane_b32 s55, v254, 25
	v_readlane_b32 s56, v254, 26
	v_readlane_b32 s57, v254, 27
	v_readlane_b32 s58, v254, 28
	v_readlane_b32 s59, v254, 29
	v_readlane_b32 s60, v254, 30
	v_readlane_b32 s61, v254, 31
	v_readlane_b32 s62, v254, 32
	v_readlane_b32 s63, v254, 33
	v_readlane_b32 s64, v254, 34
	v_readlane_b32 s65, v254, 35
	s_mov_b64 s[16:17], 0
	s_waitcnt vmcnt(0) lgkmcnt(0)
	v_pk_add_f32 v[164:165], v[164:165], v[138:139]
	ds_bpermute_b32 v138, v162, v92
	ds_bpermute_b32 v139, v162, v93
	v_pk_add_f32 v[166:167], v[166:167], v[156:157]
	v_pk_add_f32 v[172:173], v[172:173], v[228:229]
	v_pk_add_f32 v[174:175], v[174:175], v[230:231]
	v_pk_add_f32 v[178:179], v[178:179], v[234:235]
	v_pk_add_f32 v[176:177], v[176:177], v[232:233]
	v_pk_add_f32 v[182:183], v[182:183], v[238:239]
	v_pk_add_f32 v[180:181], v[180:181], v[236:237]
	global_store_dwordx4 v[152:153], v[164:167], off
	global_store_dwordx4 v[152:153], v[172:175], off offset:64
	global_store_dwordx4 v[152:153], v[176:179], off offset:512
	global_store_dwordx4 v[152:153], v[180:183], off offset:576
	v_pk_add_f32 v[166:167], v[186:187], v[242:243]
	v_pk_add_f32 v[164:165], v[184:185], v[240:241]
	v_pk_add_f32 v[172:173], v[188:189], v[244:245]
	v_add_co_u32_e32 v156, vcc, s40, v152
	v_pk_add_f32 v[174:175], v[190:191], v[246:247]
	v_pk_add_f32 v[178:179], v[194:195], v[250:251]
	v_pk_add_f32 v[176:177], v[192:193], v[248:249]
	global_store_dwordx4 v[136:137], v[164:167], off
	global_store_dwordx4 v[136:137], v[172:175], off offset:64
	global_store_dwordx4 v[136:137], v[176:179], off offset:512
	v_addc_co_u32_e32 v157, vcc, 0, v153, vcc
	ds_bpermute_b32 v172, v162, v98
	ds_bpermute_b32 v173, v162, v99
	v_pk_add_f32 v[134:135], v[134:135], v[252:253]
	global_load_dwordx4 v[164:167], v[156:157], off
	s_waitcnt lgkmcnt(2)
	v_pk_add_f32 v[132:133], v[132:133], v[138:139]
	global_store_dwordx4 v[136:137], v[132:135], off offset:576
	ds_bpermute_b32 v132, v162, v96
	ds_bpermute_b32 v133, v162, v97
	ds_bpermute_b32 v136, v162, v90
	ds_bpermute_b32 v137, v162, v91
	ds_bpermute_b32 v138, v162, v88
	ds_bpermute_b32 v139, v162, v89
	s_waitcnt lgkmcnt(6)
	v_pk_add_f32 v[134:135], v[198:199], v[172:173]
	global_load_dwordx4 v[172:175], v[156:157], off offset:64
	s_waitcnt lgkmcnt(4)
	v_pk_add_f32 v[132:133], v[196:197], v[132:133]
	global_store_dwordx4 v[208:209], v[132:135], off
	ds_bpermute_b32 v180, v162, v76
	ds_bpermute_b32 v182, v162, v78
	s_waitcnt lgkmcnt(4)
	v_pk_add_f32 v[134:135], v[202:203], v[136:137]
	ds_bpermute_b32 v136, v162, v86
	ds_bpermute_b32 v137, v162, v87
	s_waitcnt lgkmcnt(4)
	v_pk_add_f32 v[132:133], v[200:201], v[138:139]
	ds_bpermute_b32 v138, v162, v84
	ds_bpermute_b32 v139, v162, v85
	global_store_dwordx4 v[208:209], v[132:135], off offset:64
	global_load_dwordx4 v[132:135], v[156:157], off offset:512
	s_waitcnt lgkmcnt(2)
	v_pk_add_f32 v[178:179], v[206:207], v[136:137]
	ds_bpermute_b32 v183, v162, v79
	s_waitcnt lgkmcnt(1)
	v_pk_add_f32 v[176:177], v[204:205], v[138:139]
	global_load_dwordx4 v[136:139], v[156:157], off offset:576
	ds_bpermute_b32 v181, v162, v77
	global_store_dwordx4 v[208:209], v[176:179], off offset:512
	v_add_co_u32_e32 v204, vcc, s41, v152
	s_waitcnt lgkmcnt(1)
	v_pk_add_f32 v[178:179], v[214:215], v[182:183]
	s_waitcnt lgkmcnt(0)
	v_pk_add_f32 v[176:177], v[212:213], v[180:181]
	ds_bpermute_b32 v180, v162, v80
	ds_bpermute_b32 v181, v162, v81
	ds_bpermute_b32 v182, v162, v82
	ds_bpermute_b32 v183, v162, v83
	v_addc_co_u32_e32 v205, vcc, 0, v153, vcc
	global_store_dwordx4 v[208:209], v[176:179], off offset:576
	global_load_dwordx4 v[176:179], v[204:205], off
	s_waitcnt lgkmcnt(0)
	v_pk_add_f32 v[182:183], v[218:219], v[182:183]
	global_load_dwordx4 v[184:187], v[204:205], off offset:64
	v_pk_add_f32 v[180:181], v[216:217], v[180:181]
	ds_bpermute_b32 v188, v162, v74
	ds_bpermute_b32 v189, v162, v75
	global_store_dwordx4 v[154:155], v[180:183], off
	ds_bpermute_b32 v180, v162, v72
	ds_bpermute_b32 v181, v162, v73
	ds_bpermute_b32 v192, v162, v68
	s_waitcnt lgkmcnt(3)
	v_pk_add_f32 v[182:183], v[222:223], v[188:189]
	global_load_dwordx4 v[188:191], v[204:205], off offset:512
	ds_bpermute_b32 v193, v162, v69
	s_waitcnt lgkmcnt(2)
	v_pk_add_f32 v[180:181], v[220:221], v[180:181]
	ds_bpermute_b32 v194, v162, v70
	ds_bpermute_b32 v195, v162, v71
	global_store_dwordx4 v[154:155], v[180:183], off offset:64
	global_load_dwordx4 v[180:183], v[204:205], off offset:576
	ds_bpermute_b32 v200, v162, v64
	ds_bpermute_b32 v196, v162, v66
	ds_bpermute_b32 v197, v162, v67
	ds_bpermute_b32 v201, v162, v65
	v_add_co_u32_e32 v206, vcc, s42, v152
	s_waitcnt lgkmcnt(4)
	v_pk_add_f32 v[194:195], v[226:227], v[194:195]
	v_pk_add_f32 v[192:193], v[224:225], v[192:193]
	v_addc_co_u32_e32 v207, vcc, 0, v153, vcc
	global_store_dwordx4 v[154:155], v[192:195], off offset:512
	global_load_dwordx4 v[192:195], v[206:207], off
	s_waitcnt lgkmcnt(1)
	v_pk_add_f32 v[130:131], v[130:131], v[196:197]
	s_waitcnt lgkmcnt(0)
	v_pk_add_f32 v[128:129], v[128:129], v[200:201]
	global_load_dwordx4 v[196:199], v[206:207], off offset:64
	ds_bpermute_b32 v202, v162, v62
	ds_bpermute_b32 v203, v162, v63
	global_store_dwordx4 v[154:155], v[128:131], off offset:576
	ds_bpermute_b32 v128, v162, v60
	ds_bpermute_b32 v129, v162, v61
	ds_bpermute_b32 v208, v162, v58
	ds_bpermute_b32 v209, v162, v59
	s_waitcnt vmcnt(18) lgkmcnt(4)
	v_pk_add_f32 v[130:131], v[166:167], v[202:203]
	ds_bpermute_b32 v154, v162, v56
	global_load_dwordx4 v[200:203], v[206:207], off offset:512
	ds_bpermute_b32 v155, v162, v57
	s_waitcnt lgkmcnt(4)
	v_pk_add_f32 v[128:129], v[164:165], v[128:129]
	global_load_dwordx4 v[164:167], v[206:207], off offset:576
	ds_bpermute_b32 v212, v162, v44
	global_store_dwordx4 v[156:157], v[128:131], off
	ds_bpermute_b32 v214, v162, v46
	ds_bpermute_b32 v215, v162, v47
	s_waitcnt vmcnt(19) lgkmcnt(5)
	v_pk_add_f32 v[130:131], v[174:175], v[208:209]
	v_add_co_u32_e32 v208, vcc, s43, v152
	s_waitcnt lgkmcnt(3)
	v_pk_add_f32 v[128:129], v[172:173], v[154:155]
	v_addc_co_u32_e32 v209, vcc, 0, v153, vcc
	global_store_dwordx4 v[156:157], v[128:131], off offset:64
	ds_bpermute_b32 v172, v162, v48
	ds_bpermute_b32 v173, v162, v49
	global_load_dwordx4 v[128:131], v[208:209], off
	global_load_dwordx4 v[152:155], v[208:209], off offset:64
	ds_bpermute_b32 v174, v162, v50
	ds_bpermute_b32 v175, v162, v51
	ds_bpermute_b32 v213, v162, v45
	s_waitcnt vmcnt(19) lgkmcnt(3)
	v_pk_add_f32 v[132:133], v[132:133], v[172:173]
	ds_bpermute_b32 v172, v162, v54
	ds_bpermute_b32 v173, v162, v55
	s_waitcnt lgkmcnt(3)
	v_pk_add_f32 v[134:135], v[134:135], v[174:175]
	global_store_dwordx4 v[156:157], v[132:135], off offset:512
	s_waitcnt vmcnt(16) lgkmcnt(0)
	v_pk_add_f32 v[174:175], v[178:179], v[172:173]
	v_pk_add_f32 v[134:135], v[138:139], v[214:215]
	v_pk_add_f32 v[132:133], v[136:137], v[212:213]
	global_store_dwordx4 v[156:157], v[132:135], off offset:576
	global_load_dwordx4 v[132:135], v[208:209], off offset:512
	ds_bpermute_b32 v156, v162, v52
	global_load_dwordx4 v[136:139], v[208:209], off offset:576
	ds_bpermute_b32 v157, v162, v53
	ds_bpermute_b32 v212, v162, v40
	ds_bpermute_b32 v214, v162, v42
	ds_bpermute_b32 v215, v162, v43
	ds_bpermute_b32 v213, v162, v41
	s_waitcnt lgkmcnt(4)
	v_pk_add_f32 v[172:173], v[176:177], v[156:157]
	global_store_dwordx4 v[204:205], v[172:175], off
	ds_bpermute_b32 v156, v162, v32
	ds_bpermute_b32 v157, v162, v33
	s_waitcnt vmcnt(19) lgkmcnt(3)
	v_pk_add_f32 v[174:175], v[186:187], v[214:215]
	s_waitcnt lgkmcnt(2)
	v_pk_add_f32 v[172:173], v[184:185], v[212:213]
	global_store_dwordx4 v[204:205], v[172:175], off offset:64
	ds_bpermute_b32 v172, v162, v34
	ds_bpermute_b32 v173, v162, v35
	ds_bpermute_b32 v176, v162, v28
	ds_bpermute_b32 v178, v162, v30
	ds_bpermute_b32 v179, v162, v31
	ds_bpermute_b32 v177, v162, v29
	s_waitcnt vmcnt(18) lgkmcnt(4)
	v_pk_add_f32 v[174:175], v[190:191], v[172:173]
	v_pk_add_f32 v[172:173], v[188:189], v[156:157]
	global_store_dwordx4 v[204:205], v[172:175], off offset:512
	ds_bpermute_b32 v156, v162, v36
	ds_bpermute_b32 v157, v162, v37
	s_waitcnt vmcnt(17) lgkmcnt(3)
	v_pk_add_f32 v[174:175], v[182:183], v[178:179]
	s_waitcnt lgkmcnt(2)
	v_pk_add_f32 v[172:173], v[180:181], v[176:177]
	global_store_dwordx4 v[204:205], v[172:175], off offset:576
	ds_bpermute_b32 v172, v162, v38
	ds_bpermute_b32 v173, v162, v39
	ds_bpermute_b32 v176, v162, v24
	ds_bpermute_b32 v178, v162, v26
	ds_bpermute_b32 v179, v162, v27
	ds_bpermute_b32 v177, v162, v25
	s_waitcnt vmcnt(16) lgkmcnt(4)
	v_pk_add_f32 v[174:175], v[194:195], v[172:173]
	v_pk_add_f32 v[172:173], v[192:193], v[156:157]
	global_store_dwordx4 v[206:207], v[172:175], off
	ds_bpermute_b32 v156, v162, v16
	ds_bpermute_b32 v157, v162, v17
	s_waitcnt vmcnt(16) lgkmcnt(3)
	v_pk_add_f32 v[174:175], v[198:199], v[178:179]
	s_waitcnt lgkmcnt(2)
	v_pk_add_f32 v[172:173], v[196:197], v[176:177]
	ds_bpermute_b32 v176, v162, v12
	ds_bpermute_b32 v178, v162, v14
	ds_bpermute_b32 v179, v162, v15
	ds_bpermute_b32 v177, v162, v13
	global_store_dwordx4 v[206:207], v[172:175], off offset:64
	ds_bpermute_b32 v172, v162, v18
	ds_bpermute_b32 v173, v162, v19
	s_waitcnt vmcnt(14) lgkmcnt(3)
	v_pk_add_f32 v[166:167], v[166:167], v[178:179]
	s_waitcnt lgkmcnt(2)
	v_pk_add_f32 v[164:165], v[164:165], v[176:177]
	global_store_dwordx4 v[206:207], v[164:167], off offset:576
	ds_bpermute_b32 v164, v162, v22
	s_waitcnt lgkmcnt(1)
	v_pk_add_f32 v[174:175], v[202:203], v[172:173]
	v_pk_add_f32 v[172:173], v[200:201], v[156:157]
	ds_bpermute_b32 v156, v162, v20
	ds_bpermute_b32 v157, v162, v21
	ds_bpermute_b32 v165, v162, v23
	global_store_dwordx4 v[206:207], v[172:175], off offset:512
	ds_bpermute_b32 v166, v162, v8
	ds_bpermute_b32 v172, v162, v10
	ds_bpermute_b32 v173, v162, v11
	ds_bpermute_b32 v167, v162, v9
	s_waitcnt vmcnt(13) lgkmcnt(4)
	v_pk_add_f32 v[130:131], v[130:131], v[164:165]
	v_pk_add_f32 v[128:129], v[128:129], v[156:157]
	global_store_dwordx4 v[208:209], v[128:131], off
	s_waitcnt vmcnt(13) lgkmcnt(1)
	s_nop 0
	v_pk_add_f32 v[130:131], v[154:155], v[172:173]
	s_waitcnt lgkmcnt(0)
	v_pk_add_f32 v[128:129], v[152:153], v[166:167]
	global_store_dwordx4 v[208:209], v[128:131], off offset:64
	ds_bpermute_b32 v128, v162, v4
	ds_bpermute_b32 v129, v162, v5
	ds_bpermute_b32 v130, v162, v6
	ds_bpermute_b32 v131, v162, v7
	ds_bpermute_b32 v152, v162, v0
	ds_bpermute_b32 v154, v162, v2
	ds_bpermute_b32 v155, v162, v3
	ds_bpermute_b32 v153, v162, v1
	s_waitcnt vmcnt(11) lgkmcnt(4)
	v_pk_add_f32 v[130:131], v[134:135], v[130:131]
	v_pk_add_f32 v[128:129], v[132:133], v[128:129]
	global_store_dwordx4 v[208:209], v[128:131], off offset:512
	s_waitcnt vmcnt(11) lgkmcnt(1)
	s_nop 0
	v_pk_add_f32 v[130:131], v[138:139], v[154:155]
	s_waitcnt lgkmcnt(0)
	v_pk_add_f32 v[128:129], v[136:137], v[152:153]
	global_store_dwordx4 v[208:209], v[128:131], off offset:576
